# attention loops: Q-fragment vmcnt waits hoisted out of the loops (K/V prefetch stays in flight), 3-buffer K/V ring with wave-group-shifted barrier so SIMD partner waves are out of phase
# speedup vs baseline: 1.0150x; 1.0150x over previous
; #define LAS __attribute__((address_space(3)))
; template <int DK, bool IS_A>
; __device__ __forceinline__ void attn_unit(const Params& P, int l, LAS unsigned char* lds, int b, int grp, int qtok0, int nkeys) {
;     const int tid = opaque_tid(), lane = tid & 63, wave = tid >> 6, s = wave >> 2, wq = wave & 3, r32 = lane & 31, hi = lane >> 5;
;     const bf16_t* proj = (const bf16_t*)(P.ws + WS_PROJ);
;     bf16_t* mix = (bf16_t*)(P.ws + WS_H);
;     const int qcol = IS_A ? PA_Q + grp * 64 + s * 32 : PC_Q + (2 * grp + s) * 64;
;     const int kcol = IS_A ? PA_K + grp * 64 : PC_K + grp * 64;
;     const int koff = IS_A ? s * 32 : 0;
;     const bf16_t* VT = IS_A ? (const bf16_t*)(P.ws + WS_VTA) + ((size_t)(b * 4 + grp) * 64) * TT : (const bf16_t*)(P.ws + WS_VTC) + ((size_t)(b * 2 + grp) * 64) * TT;
;     const size_t qrow = (size_t)b * TT + qtok0 + wq * 64 + r32;
;     bf16x8 qa[DK / 16], qb[DK / 16];
; #pragma unroll
;     for (int i = 0; i < DK / 16; ++i) { qa[i] = *(const bf16x8*)(proj + qrow * INW + qcol + i * 16 + hi * 8); qb[i] = *(const bf16x8*)(proj + (qrow + 32) * INW + qcol + i * 16 + hi * 8); }
;     const int lrow = tid >> 3, lch = tid & 7;
;     const bf16_t* ksrc = proj + ((size_t)b * TT + lrow) * INW + kcol + lch * 8;
;     const bf16_t* vsrc = VT + (size_t)lrow * TT + lch * 8;
;     const int NT = nkeys / AKT;
;     u32x4 kreg0, kreg1, vreg0, vreg1;
;     ...
;     const int kfo = r32 * AK_PITCH + (koff + 8 * hi) * 2, vfo = AK_BYTES + r32 * AV_PITCH + 8 * hi;
;     AT_LOAD(0); AT_STORE(0);
;     __syncthreads();
;     float ma = -1e30f, mb = -1e30f, la = 0.f, lb_ = 0.f;
;     f32x16 oa0, oa1, ob0, ob1;
; #pragma unroll
;     for (int r = 0; r < 16; ++r) { oa0[r] = 0.f; oa1[r] = 0.f; ob0[r] = 0.f; ob1[r] = 0.f; }
;     ...
;     for (;;) {
;         if (opaque_tid() == 0) *slot = (int)atomicAdd(ctr, 1u);
;         __syncthreads();
;         int it = *slot;
;         __syncthreads();
;         if (it >= total) break;
;         if (it < N_F) {
;             pg8::Gemm g{(const pg8::bf16_t*)(P.ws + WS_FMAT), (const pg8::bf16_t*)(P.ws + WS_ZT), SEQ, NBATCH * 256, 2048}; OneUnit S{it & 7, it >> 3};
;             pg8::EpiBf16<0> E{(pg8::bf16_t*)(P.ws + WS_H) + (size_t)CTX * DM + 768, DM, nullptr, 256, (size_t)TT * DM, 1.0f};
;             pg8::gemm_phase<pg8::EpiBf16<0>, OneUnit, false, true>(lds, g, S, E); __syncthreads(); continue; } it -= N_F;
.LBB0_355:
	s_or_b64 exec, exec, s[10:11]
	v_readlane_b32 s7, v254, 26
	s_waitcnt lgkmcnt(0)
	s_barrier
	v_mov_b32_e32 v0, s7
	ds_read_b32 v0, v0
	s_mov_b64 s[10:11], -1
	s_waitcnt lgkmcnt(0)
	s_barrier
	v_cmp_le_i32_e32 vcc, s29, v0
	v_readfirstlane_b32 s37, v0
	s_cbranch_vccnz .LBB0_350
	s_cmpk_gt_i32 s37, 0x7f
	s_cbranch_scc0 .LBB0_720
	s_cmpk_gt_u32 s37, 0x9f
	s_cbranch_scc0 .LBB0_461
	s_cmpk_gt_u32 s37, 0x19f
	s_cbranch_scc0 .LBB0_440
	s_cmpk_gt_u32 s37, 0x39f
	s_cbranch_scc0 .LBB0_415
	s_cmpk_gt_u32 s37, 0x3af
	s_cbranch_scc0 .LBB0_406
	s_cmpk_gt_u32 s37, 0x3ef
	s_cbranch_scc0 .LBB0_381
	s_add_i32 s8, s37, 0xfffffc10
	s_lshr_b32 s9, s8, 1
	s_and_b32 s10, s37, 1
	v_mov_b32_e32 v12, v200
	s_lshl_b32 s8, s10, 7
	s_lshl_b32 s10, s10, 6
	s_lshl_b32 s11, s9, 7
	s_or_b32 s10, s11, s10
	v_ashrrev_i32_e32 v2, 3, v12
	s_mul_i32 s64, s10, 0x900
	s_mul_i32 s10, s9, 0x900
	s_mov_b32 s11, s65
	v_ashrrev_i32_e32 v3, 31, v2
	v_mov_b64_e32 v[0:1], s[56:57]
	s_lshl_b64 s[12:13], s[64:65], 1
	v_lshl_add_u64 v[4:5], v[2:3], 0, s[10:11]
	s_add_u32 s12, s20, s12
	v_readlane_b32 s7, v255, 5
	v_mad_u64_u32 v[6:7], s[18:19], v4, s23, v[0:1]
	s_addc_u32 s13, s7, s13
	v_mad_i32_i24 v7, v5, s23, v7
	s_mov_b32 s9, s65
	v_lshlrev_b32_e32 v3, 4, v12
	v_lshl_add_u64 v[4:5], v[6:7], 0, s[8:9]
	v_and_b32_e32 v190, 0x70, v3
	v_mov_b32_e32 v191, v129
	v_mov_b64_e32 v[6:7], s[12:13]
	v_lshl_add_u64 v[4:5], v[4:5], 0, v[190:191]
	v_mad_i64_i32 v[6:7], s[12:13], v2, s27, v[6:7]
	s_movk_i32 s7, 0x1000
	v_lshl_add_u64 v[192:193], v[6:7], 0, v[190:191]
	v_add_co_u32_e32 v6, vcc, s7, v4
	s_mov_b32 s9, 0x59000
	s_nop 0
	v_addc_co_u32_e32 v7, vcc, 0, v5, vcc
	v_add_co_u32_e32 v8, vcc, s9, v4
	v_and_b32_e32 v3, 0xc0, v12
	s_nop 0
	v_addc_co_u32_e32 v9, vcc, 0, v5, vcc
	global_load_dwordx4 v[130:133], v[6:7], off offset:512
	global_load_dwordx4 v[134:137], v[8:9], off offset:512
	global_load_dwordx4 v[138:141], v[192:193], off
	global_load_dwordx4 v[142:145], v[192:193], off offset:128
	v_ashrrev_i32_e32 v6, 2, v12
	v_and_b32_e32 v13, 31, v12
	v_and_b32_e32 v6, 0xffffffc0, v6
	v_add_u32_e32 v188, s8, v6
	v_or3_b32 v128, v3, s10, v13
	v_bfe_u32 v14, v12, 5, 1
	v_mad_u64_u32 v[0:1], s[8:9], v128, s23, v[0:1]
	v_ashrrev_i32_e32 v189, 31, v188
	v_lshl_add_u64 v[0:1], v[188:189], 1, v[0:1]
	v_lshlrev_b32_e32 v194, 4, v14
	v_mov_b32_e32 v195, v129
	v_lshl_add_u64 v[0:1], v[0:1], 0, v[194:195]
	s_mov_b64 s[8:9], 0x1000
	v_add_co_u32_e32 v10, vcc, s7, v0
	v_lshl_add_u64 v[6:7], v[0:1], 0, s[8:9]
	s_mov_b64 s[8:9], 0x2d000
	v_addc_co_u32_e32 v11, vcc, 0, v1, vcc
	s_mov_b32 s7, 0x2d000
	v_lshl_add_u64 v[8:9], v[0:1], 0, s[8:9]
	v_add_co_u32_e32 v0, vcc, s7, v0
	s_movk_i32 s7, 0x90
	s_nop 0
	v_addc_co_u32_e32 v1, vcc, 0, v1, vcc
	global_load_dwordx4 v[146:149], v[10:11], off
	global_load_dwordx4 v[150:153], v[0:1], off
	global_load_dwordx4 v[154:157], v[6:7], off offset:32
	global_load_dwordx4 v[158:161], v[6:7], off offset:64
	global_load_dwordx4 v[162:165], v[8:9], off offset:32
	global_load_dwordx4 v[166:169], v[6:7], off offset:96
	global_load_dwordx4 v[170:173], v[8:9], off offset:64
	global_load_dwordx4 v[174:177], v[8:9], off offset:96
	v_mul_lo_u32 v0, v2, s7
	s_movk_i32 s7, 0x78
	v_and_b32_e32 v1, 63, v12
	v_mul_lo_u32 v3, v2, s7
	v_add_u32_e32 v0, 0, v0
	v_add_u32_e32 v6, v0, v190
	v_add_u32_e32 v0, v0, v3
	s_mov_b64 s[10:11], 0x1200
	v_lshlrev_b32_e32 v1, 2, v1
	s_movk_i32 s7, 0xff88
	v_add_u32_e32 v7, v0, v190
	v_lshl_add_u64 v[196:197], v[4:5], 0, s[10:11]
	v_mad_u64_u32 v[198:199], s[10:11], v2, s7, v[0:1]
	v_lshlrev_b32_e32 v186, 3, v14
	v_add_u32_e32 v8, 0x4800, v7
	v_add_u32_e32 v7, 0x4880, v7
	v_add_u32_e32 v16, v198, v3
	v_mov_b32_e32 v14, v129
	v_mov_b32_e32 v15, v129
	s_waitcnt vmcnt(17)
	v_mul_u32_u24_e32 v178, 0x90, v13
	s_waitcnt vmcnt(11)
	ds_write_b128 v6, v[130:133]
	s_waitcnt vmcnt(10)
	ds_write_b128 v6, v[134:137] offset:9216
	s_waitcnt vmcnt(9)
	ds_write2_b64 v8, v[138:139], v[140:141] offset1:1
	s_waitcnt vmcnt(8)
	ds_write2_b64 v7, v[142:143], v[144:145] offset1:1
	v_mul_u32_u24_e32 v180, 0x108, v13
	v_xor_b32_e32 v179, 0x80, v1
	v_mov_b32_e32 v0, v129
	v_mov_b32_e32 v1, v129
	v_mov_b32_e32 v2, v129
	v_mov_b32_e32 v3, v129
	v_mov_b32_e32 v4, v129
	v_mov_b32_e32 v5, v129
	v_mov_b32_e32 v6, v129
	v_mov_b32_e32 v7, v129
	v_mov_b32_e32 v8, v129
	v_mov_b32_e32 v9, v129
	v_mov_b32_e32 v10, v129
	v_mov_b32_e32 v11, v129
	v_mov_b32_e32 v12, v129
	v_mov_b32_e32 v13, v129
	v_add_u32_e32 v181, v16, v190
	v_mov_b64_e32 v[30:31], v[14:15]
	v_mov_b64_e32 v[46:47], v[14:15]
	v_mov_b64_e32 v[62:63], v[14:15]
	s_mov_b32 s9, 0
	s_mov_b64 s[10:11], -1
	v_mov_b32_e32 v191, 0
	v_mov_b32_e32 v185, 0xf149f2ca
	v_mov_b32_e32 v187, 0xf149f2ca
	v_mov_b32_e32 v182, 0
	v_mov_b64_e32 v[28:29], v[12:13]
	v_mov_b64_e32 v[26:27], v[10:11]
	v_mov_b64_e32 v[24:25], v[8:9]
	v_mov_b64_e32 v[22:23], v[6:7]
	v_mov_b64_e32 v[20:21], v[4:5]
	v_mov_b64_e32 v[18:19], v[2:3]
	v_mov_b64_e32 v[16:17], v[0:1]
	v_mov_b64_e32 v[44:45], v[12:13]
	v_mov_b64_e32 v[42:43], v[10:11]
	v_mov_b64_e32 v[40:41], v[8:9]
	v_mov_b64_e32 v[38:39], v[6:7]
	v_mov_b64_e32 v[36:37], v[4:5]
	v_mov_b64_e32 v[34:35], v[2:3]
	v_mov_b64_e32 v[32:33], v[0:1]
	v_mov_b64_e32 v[60:61], v[12:13]
	v_mov_b64_e32 v[58:59], v[10:11]
	v_mov_b64_e32 v[56:57], v[8:9]
	v_mov_b64_e32 v[54:55], v[6:7]
	v_mov_b64_e32 v[52:53], v[4:5]
	v_mov_b64_e32 v[50:51], v[2:3]
	v_mov_b64_e32 v[48:49], v[0:1]
	s_waitcnt lgkmcnt(0)
	s_waitcnt vmcnt(0)
	s_barrier
	s_branch .LBB0_364

; #define LAS __attribute__((address_space(3)))
; template <int DK, bool IS_A>
; __device__ __forceinline__ void attn_unit(const Params& P, int l, LAS unsigned char* lds, int b, int grp, int qtok0, int nkeys) {
;     ...
;             const LAS unsigned char* kb = lds + buf * A_BUF + kfo + h * 64 * AK_PITCH;
;             const LAS unsigned char* vb = lds + buf * A_BUF + vfo + h * 128;
;             f32x16 pa[2], pb[2];
; #pragma unroll
;             for (int jj = 0; jj < 2; ++jj)
; #pragma unroll
;                 for (int r = 0; r < 16; ++r) { pa[jj][r] = 0.f; pb[jj][r] = 0.f; }
;             __builtin_amdgcn_s_setprio(1);
; #pragma unroll
;             for (int i = 0; i < DK / 16; ++i)
; #pragma unroll
;                 for (int jj = 0; jj < 2; ++jj) {
;                     const bf16x8 kf = *(const LAS bf16x8*)(kb + jj * 32 * AK_PITCH + i * 32);
;                     pa[jj] = __builtin_amdgcn_mfma_f32_32x32x16_bf16(kf, qa[i], pa[jj], 0, 0, 0);
;                     pb[jj] = __builtin_amdgcn_mfma_f32_32x32x16_bf16(kf, qb[i], pb[jj], 0, 0, 0);
;                 }
;             __builtin_amdgcn_s_setprio(0);
.LBB0_366:
	s_bitcmp1_b32 s9, 0
	s_cselect_b32 s9, 0x8a00, 0
	s_add_i32 s9, s9, 0
	v_add_u32_e32 v64, s9, v178
	v_add_u32_e32 v195, v64, v194
	s_setprio 1
	ds_read_b128 v[64:67], v195
	ds_read_b128 v[204:207], v195 offset:32
	s_waitcnt lgkmcnt(1)
	v_mfma_f32_32x32x16_bf16 v[112:127], v[64:67], v[146:149], 0
	v_mfma_f32_32x32x16_bf16 v[96:111], v[64:67], v[150:153], 0
	ds_read_b128 v[64:67], v195 offset:4608
	s_waitcnt lgkmcnt(1)
	v_mfma_f32_32x32x16_bf16 v[112:127], v[204:207], v[154:157], v[112:127]
	v_mfma_f32_32x32x16_bf16 v[96:111], v[204:207], v[162:165], v[96:111]
	ds_read_b128 v[204:207], v195 offset:4640
	s_waitcnt lgkmcnt(1)
	v_mfma_f32_32x32x16_bf16 v[80:95], v[64:67], v[146:149], 0
	v_mfma_f32_32x32x16_bf16 v[64:79], v[64:67], v[150:153], 0
	s_waitcnt lgkmcnt(0)
	v_mfma_f32_32x32x16_bf16 v[80:95], v[204:207], v[154:157], v[80:95]
	v_mfma_f32_32x32x16_bf16 v[64:79], v[204:207], v[162:165], v[64:79]
	ds_read_b128 v[204:207], v195 offset:64
	s_waitcnt lgkmcnt(0)
	v_mfma_f32_32x32x16_bf16 v[112:127], v[204:207], v[158:161], v[112:127]
	v_mfma_f32_32x32x16_bf16 v[96:111], v[204:207], v[170:173], v[96:111]
	ds_read_b128 v[204:207], v195 offset:4672
	s_waitcnt lgkmcnt(0)
	v_mfma_f32_32x32x16_bf16 v[80:95], v[204:207], v[158:161], v[80:95]
	v_mfma_f32_32x32x16_bf16 v[64:79], v[204:207], v[170:173], v[64:79]
	ds_read_b128 v[204:207], v195 offset:96
	s_waitcnt lgkmcnt(0)
	v_mfma_f32_32x32x16_bf16 v[112:127], v[204:207], v[166:169], v[112:127]
	v_mfma_f32_32x32x16_bf16 v[96:111], v[204:207], v[174:177], v[96:111]
	ds_read_b128 v[204:207], v195 offset:4704
	s_waitcnt lgkmcnt(0)
	v_mfma_f32_32x32x16_bf16 v[80:95], v[204:207], v[166:169], v[80:95]
	v_mfma_f32_32x32x16_bf16 v[64:79], v[204:207], v[174:177], v[64:79]
	s_setprio 0
	s_nop 9
	v_max_f32_e32 v183, v80, v80
	v_max_f32_e32 v184, v112, v112
	v_max_f32_e32 v183, v184, v183
	v_max3_f32 v184, v81, v114, v82
	v_max3_f32 v183, v183, v113, v115
	v_max3_f32 v184, v184, v116, v84
	v_max3_f32 v183, v183, v83, v117
	v_max3_f32 v184, v184, v118, v86
	v_max3_f32 v183, v183, v85, v119
	v_max3_f32 v184, v184, v120, v88
	v_max3_f32 v183, v183, v87, v121
	v_max3_f32 v184, v184, v122, v90
	v_max3_f32 v183, v183, v89, v123
	v_max3_f32 v184, v184, v124, v92
	v_max3_f32 v183, v183, v91, v125
	v_max3_f32 v184, v184, v126, v94
	v_max3_f32 v183, v183, v93, v127
	v_max3_f32 v183, v183, v95, v184
	ds_bpermute_b32 v184, v179, v183
	s_waitcnt lgkmcnt(0)
	v_max3_f32 v204, v185, v183, v184
	v_cmp_gt_f32_e32 vcc, v204, v185
	s_cbranch_vccz .LBB0_368
	v_sub_f32_e32 v183, v185, v204
	v_exp_f32_e32 v184, v183
	s_nop 0
	v_pk_mul_f32 v[62:63], v[62:63], v[184:185] op_sel_hi:[1,0]
	v_pk_mul_f32 v[60:61], v[60:61], v[184:185] op_sel_hi:[1,0]
	v_pk_mul_f32 v[58:59], v[58:59], v[184:185] op_sel_hi:[1,0]
	v_pk_mul_f32 v[56:57], v[56:57], v[184:185] op_sel_hi:[1,0]
	v_pk_mul_f32 v[54:55], v[54:55], v[184:185] op_sel_hi:[1,0]
	v_pk_mul_f32 v[52:53], v[52:53], v[184:185] op_sel_hi:[1,0]
	v_pk_mul_f32 v[50:51], v[50:51], v[184:185] op_sel_hi:[1,0]
	v_pk_mul_f32 v[48:49], v[48:49], v[184:185] op_sel_hi:[1,0]
	v_pk_mul_f32 v[46:47], v[46:47], v[184:185] op_sel_hi:[1,0]
	v_pk_mul_f32 v[44:45], v[44:45], v[184:185] op_sel_hi:[1,0]
	v_pk_mul_f32 v[42:43], v[42:43], v[184:185] op_sel_hi:[1,0]
	v_pk_mul_f32 v[40:41], v[40:41], v[184:185] op_sel_hi:[1,0]
	v_pk_mul_f32 v[38:39], v[38:39], v[184:185] op_sel_hi:[1,0]
	v_pk_mul_f32 v[36:37], v[36:37], v[184:185] op_sel_hi:[1,0]
	v_pk_mul_f32 v[34:35], v[34:35], v[184:185] op_sel_hi:[1,0]
	v_pk_mul_f32 v[32:33], v[32:33], v[184:185] op_sel_hi:[1,0]
	v_mul_f32_e32 v191, v191, v184
	s_branch .LBB0_369

; #define LAS __attribute__((address_space(3)))
; __device__ __forceinline__ unsigned pk2(float lo, float hi) { f32x2_t v = {lo, hi}; bf16x2_t b = __builtin_convertvector(v, bf16x2_t); return __builtin_bit_cast(unsigned, b); }
; template <int DK, bool IS_A>
; __device__ __forceinline__ void attn_unit(const Params& P, int l, LAS unsigned char* lds, int b, int grp, int qtok0, int nkeys) {
;     ...
;             AT_SOFTMAX(pa, ma, la, oa0, oa1);
;             AT_SOFTMAX(pb, mb, lb_, ob0, ob1);
;     ...
; #pragma unroll
;             for (int ks = 0; ks < 4; ++ks) {
;                 const int o8 = 8 * (ks & 1);
;                 u32x4 w; const f32x16& xa = pa[ks >> 1]; const f32x16& xb = pb[ks >> 1];
;                 w.x = pk2(xa[o8], xa[o8 + 1]); w.y = pk2(xa[o8 + 2], xa[o8 + 3]); w.z = pk2(xa[o8 + 4], xa[o8 + 5]); w.w = pk2(xa[o8 + 6], xa[o8 + 7]);
;                 const bf16x8 pfa = __builtin_bit_cast(bf16x8, w);
;                 w.x = pk2(xb[o8], xb[o8 + 1]); w.y = pk2(xb[o8 + 2], xb[o8 + 3]); w.z = pk2(xb[o8 + 4], xb[o8 + 5]); w.w = pk2(xb[o8 + 6], xb[o8 + 7]);
;                 const bf16x8 pfb = __builtin_bit_cast(bf16x8, w);
;                 const u32x2 a0 = *(const LAS u32x2*)(vb + ks * 32), a1 = *(const LAS u32x2*)(vb + ks * 32 + 16);
;                 const u32x2 c0 = *(const LAS u32x2*)(vb + 32 * AV_PITCH + ks * 32), c1 = *(const LAS u32x2*)(vb + 32 * AV_PITCH + ks * 32 + 16);
;                 const bf16x8 v0 = __builtin_bit_cast(bf16x8, ((u32x4){a0.x, a0.y, a1.x, a1.y})), v1 = __builtin_bit_cast(bf16x8, ((u32x4){c0.x, c0.y, c1.x, c1.y}));
;                 oa0 = __builtin_amdgcn_mfma_f32_32x32x16_bf16(v0, pfa, oa0, 0, 0, 0);
;                 oa1 = __builtin_amdgcn_mfma_f32_32x32x16_bf16(v1, pfa, oa1, 0, 0, 0);
;                 ob0 = __builtin_amdgcn_mfma_f32_32x32x16_bf16(v0, pfb, ob0, 0, 0, 0);
;                 ob1 = __builtin_amdgcn_mfma_f32_32x32x16_bf16(v1, pfb, ob1, 0, 0, 0);
;             }
;         }
;         if (t + 1 < NT) AT_STORE(buf ^ 1);
;         __syncthreads();
.LBB0_378:
	ds_read2_b64 v[204:207], v183 offset0:16 offset1:18
	ds_read2_b64 v[212:215], v184 offset0:48 offset1:50
	v_sub_f32_e32 v112, v112, v185
	v_sub_f32_e32 v113, v113, v185
	v_sub_f32_e32 v114, v114, v185
	v_sub_f32_e32 v115, v115, v185
	v_sub_f32_e32 v116, v116, v185
	v_sub_f32_e32 v117, v117, v185
	v_sub_f32_e32 v118, v118, v185
	v_sub_f32_e32 v119, v119, v185
	v_exp_f32_e32 v112, v112
	v_exp_f32_e32 v113, v113
	v_exp_f32_e32 v114, v114
	v_exp_f32_e32 v115, v115
	v_exp_f32_e32 v116, v116
	v_exp_f32_e32 v117, v117
	v_exp_f32_e32 v118, v118
	v_exp_f32_e32 v119, v119
	v_sub_f32_e32 v96, v96, v187
	v_sub_f32_e32 v97, v97, v187
	v_sub_f32_e32 v98, v98, v187
	v_sub_f32_e32 v99, v99, v187
	v_sub_f32_e32 v100, v100, v187
	v_sub_f32_e32 v101, v101, v187
	v_sub_f32_e32 v102, v102, v187
	v_sub_f32_e32 v103, v103, v187
	v_exp_f32_e32 v96, v96
	v_exp_f32_e32 v97, v97
	v_exp_f32_e32 v98, v98
	v_exp_f32_e32 v99, v99
	v_exp_f32_e32 v100, v100
	v_exp_f32_e32 v101, v101
	v_exp_f32_e32 v102, v102
	v_exp_f32_e32 v103, v103
	v_cvt_pk_bf16_f32 v208, v112, v113
	v_cvt_pk_bf16_f32 v209, v114, v115
	v_cvt_pk_bf16_f32 v210, v116, v117
	v_cvt_pk_bf16_f32 v211, v118, v119
	v_sub_f32_e32 v120, v120, v185
	v_sub_f32_e32 v121, v121, v185
	s_waitcnt lgkmcnt(1)
	v_mfma_f32_32x32x16_bf16 v[48:63], v[204:207], v[208:211], v[48:63]
	v_sub_f32_e32 v122, v122, v185
	v_sub_f32_e32 v123, v123, v185
	v_sub_f32_e32 v124, v124, v185
	v_sub_f32_e32 v125, v125, v185
	v_sub_f32_e32 v126, v126, v185
	v_sub_f32_e32 v127, v127, v185
	v_exp_f32_e32 v120, v120
	s_waitcnt lgkmcnt(0)
	v_mfma_f32_32x32x16_bf16 v[32:47], v[212:215], v[208:211], v[32:47]
	v_cvt_pk_bf16_f32 v208, v96, v97
	v_cvt_pk_bf16_f32 v209, v98, v99
	v_cvt_pk_bf16_f32 v210, v100, v101
	v_cvt_pk_bf16_f32 v211, v102, v103
	v_exp_f32_e32 v121, v121
	v_exp_f32_e32 v122, v122
	v_exp_f32_e32 v123, v123
	v_mfma_f32_32x32x16_bf16 v[16:31], v[204:207], v[208:211], v[16:31]
	ds_read2_b64 v[204:207], v183 offset0:20 offset1:22
	v_exp_f32_e32 v124, v124
	v_exp_f32_e32 v125, v125
	v_exp_f32_e32 v126, v126
	v_exp_f32_e32 v127, v127
	v_sub_f32_e32 v104, v104, v187
	v_sub_f32_e32 v105, v105, v187
	v_mfma_f32_32x32x16_bf16 v[0:15], v[212:215], v[208:211], v[0:15]
	ds_read2_b64 v[212:215], v184 offset0:52 offset1:54
	v_sub_f32_e32 v106, v106, v187
	v_sub_f32_e32 v107, v107, v187
	v_sub_f32_e32 v108, v108, v187
	v_sub_f32_e32 v109, v109, v187
	v_sub_f32_e32 v110, v110, v187
	v_sub_f32_e32 v111, v111, v187
	v_exp_f32_e32 v104, v104
	v_exp_f32_e32 v105, v105
	v_exp_f32_e32 v106, v106
	v_exp_f32_e32 v107, v107
	v_exp_f32_e32 v108, v108
	v_exp_f32_e32 v109, v109
	v_exp_f32_e32 v110, v110
	v_exp_f32_e32 v111, v111
	v_cvt_pk_bf16_f32 v208, v120, v121
	v_cvt_pk_bf16_f32 v209, v122, v123
	v_cvt_pk_bf16_f32 v210, v124, v125
	v_cvt_pk_bf16_f32 v211, v126, v127
	v_sub_f32_e32 v66, v66, v187
	v_exp_f32_e32 v195, v66
	s_waitcnt lgkmcnt(1)
	v_mfma_f32_32x32x16_bf16 v[48:63], v[204:207], v[208:211], v[48:63]
	v_sub_f32_e32 v66, v67, v187
	v_exp_f32_e32 v67, v66
	v_sub_f32_e32 v66, v68, v187
	v_exp_f32_e32 v68, v66
	v_sub_f32_e32 v66, v69, v187
	v_sub_f32_e32 v80, v80, v185
	v_sub_f32_e32 v81, v81, v185
	s_waitcnt lgkmcnt(0)
	v_mfma_f32_32x32x16_bf16 v[32:47], v[212:215], v[208:211], v[32:47]
	v_cvt_pk_bf16_f32 v208, v104, v105
	v_cvt_pk_bf16_f32 v209, v106, v107
	v_cvt_pk_bf16_f32 v210, v108, v109
	v_cvt_pk_bf16_f32 v211, v110, v111
	v_sub_f32_e32 v82, v82, v185
	v_sub_f32_e32 v83, v83, v185
	v_sub_f32_e32 v84, v84, v185
	v_mfma_f32_32x32x16_bf16 v[16:31], v[204:207], v[208:211], v[16:31]
	ds_read2_b64 v[204:207], v183 offset0:24 offset1:26
	v_sub_f32_e32 v85, v85, v185
	v_sub_f32_e32 v86, v86, v185
	v_sub_f32_e32 v87, v87, v185
	v_exp_f32_e32 v69, v66
	v_sub_f32_e32 v66, v70, v187
	v_exp_f32_e32 v80, v80
	v_mfma_f32_32x32x16_bf16 v[0:15], v[212:215], v[208:211], v[0:15]
	ds_read2_b64 v[212:215], v184 offset0:56 offset1:58
	v_exp_f32_e32 v81, v81
	v_exp_f32_e32 v82, v82
	v_exp_f32_e32 v83, v83
	v_exp_f32_e32 v84, v84
	v_exp_f32_e32 v85, v85
	v_exp_f32_e32 v86, v86
	v_exp_f32_e32 v87, v87
	v_sub_f32_e32 v64, v64, v187
	v_sub_f32_e32 v65, v65, v187
	v_exp_f32_e32 v70, v66
	v_sub_f32_e32 v66, v71, v187
	v_exp_f32_e32 v64, v64
	v_exp_f32_e32 v65, v65
	v_exp_f32_e32 v71, v66
	v_cvt_pk_bf16_f32 v208, v80, v81
	v_cvt_pk_bf16_f32 v209, v82, v83
	v_cvt_pk_bf16_f32 v210, v84, v85
	v_cvt_pk_bf16_f32 v211, v86, v87
	v_sub_f32_e32 v88, v88, v185
	v_sub_f32_e32 v89, v89, v185
	s_waitcnt lgkmcnt(1)
	v_mfma_f32_32x32x16_bf16 v[48:63], v[204:207], v[208:211], v[48:63]
	v_sub_f32_e32 v90, v90, v185
	v_sub_f32_e32 v91, v91, v185
	v_sub_f32_e32 v92, v92, v185
	v_sub_f32_e32 v93, v93, v185
	v_sub_f32_e32 v94, v94, v185
	v_sub_f32_e32 v66, v95, v185
	v_exp_f32_e32 v88, v88
	s_waitcnt lgkmcnt(0)
	v_mfma_f32_32x32x16_bf16 v[32:47], v[212:215], v[208:211], v[32:47]
	v_cvt_pk_bf16_f32 v208, v64, v65
	v_cvt_pk_bf16_f32 v209, v195, v67
	v_cvt_pk_bf16_f32 v210, v68, v69
	v_cvt_pk_bf16_f32 v211, v70, v71
	v_exp_f32_e32 v89, v89
	v_exp_f32_e32 v90, v90
	v_exp_f32_e32 v91, v91
	v_mfma_f32_32x32x16_bf16 v[16:31], v[204:207], v[208:211], v[16:31]
	ds_read2_b64 v[204:207], v183 offset0:28 offset1:30
	v_exp_f32_e32 v92, v92
	v_exp_f32_e32 v93, v93
	v_exp_f32_e32 v94, v94
	v_exp_f32_e32 v66, v66
	v_sub_f32_e32 v72, v72, v187
	v_sub_f32_e32 v73, v73, v187
	v_mfma_f32_32x32x16_bf16 v[0:15], v[212:215], v[208:211], v[0:15]
	ds_read2_b64 v[212:215], v184 offset0:60 offset1:62
	v_sub_f32_e32 v74, v74, v187
	v_sub_f32_e32 v75, v75, v187
	v_sub_f32_e32 v76, v76, v187
	v_sub_f32_e32 v77, v77, v187
	v_sub_f32_e32 v78, v78, v187
	v_sub_f32_e32 v79, v79, v187
	v_exp_f32_e32 v72, v72
	v_exp_f32_e32 v73, v73
	v_exp_f32_e32 v74, v74
	v_exp_f32_e32 v75, v75
	v_exp_f32_e32 v76, v76
	v_exp_f32_e32 v77, v77
	v_exp_f32_e32 v78, v78
	v_exp_f32_e32 v79, v79
	v_cvt_pk_bf16_f32 v208, v88, v89
	v_cvt_pk_bf16_f32 v209, v90, v91
	v_cvt_pk_bf16_f32 v210, v92, v93
	v_cvt_pk_bf16_f32 v211, v94, v66
	s_and_b64 vcc, exec, s[38:39]
	s_waitcnt lgkmcnt(1)
	v_mfma_f32_32x32x16_bf16 v[48:63], v[204:207], v[208:211], v[48:63]
	s_waitcnt lgkmcnt(0)
	v_mfma_f32_32x32x16_bf16 v[32:47], v[212:215], v[208:211], v[32:47]
	v_cvt_pk_bf16_f32 v208, v72, v73
	v_cvt_pk_bf16_f32 v209, v74, v75
	v_cvt_pk_bf16_f32 v210, v76, v77
	v_cvt_pk_bf16_f32 v211, v78, v79
	s_nop 1
	v_mfma_f32_32x32x16_bf16 v[16:31], v[204:207], v[208:211], v[16:31]
	v_mfma_f32_32x32x16_bf16 v[0:15], v[212:215], v[208:211], v[0:15]
	s_cbranch_vccnz .LBB0_363
	s_waitcnt vmcnt(0)
	v_add_u32_e32 v95, v198, v190
	ds_write_b128 v95, v[130:133] offset:35328
	ds_write_b128 v95, v[134:137] offset:44544
	v_add_u32_e32 v95, 0xd200, v181
	ds_write2_b64 v95, v[138:139], v[140:141] offset1:1
	v_add_u32_e32 v95, 0xd280, v181
	ds_write2_b64 v95, v[142:143], v[144:145] offset1:1
	s_branch .LBB0_363

; #define LAS __attribute__((address_space(3)))
; __device__ __forceinline__ int opaque_tid() { int t = threadIdx.x; asm volatile("" : "+v"(t)); return t; }
; template <int DK, bool IS_A>
; __device__ __forceinline__ void attn_unit(const Params& P, int l, LAS unsigned char* lds, int b, int grp, int qtok0, int nkeys) {
;     const int tid = opaque_tid(), lane = tid & 63, wave = tid >> 6, s = wave >> 2, wq = wave & 3, r32 = lane & 31, hi = lane >> 5;
;     const bf16_t* proj = (const bf16_t*)(P.ws + WS_PROJ);
;     bf16_t* mix = (bf16_t*)(P.ws + WS_H);
;     const int qcol = IS_A ? PA_Q + grp * 64 + s * 32 : PC_Q + (2 * grp + s) * 64;
;     const int kcol = IS_A ? PA_K + grp * 64 : PC_K + grp * 64;
;     const int koff = IS_A ? s * 32 : 0;
;     const bf16_t* VT = IS_A ? (const bf16_t*)(P.ws + WS_VTA) + ((size_t)(b * 4 + grp) * 64) * TT : (const bf16_t*)(P.ws + WS_VTC) + ((size_t)(b * 2 + grp) * 64) * TT;
;     const size_t qrow = (size_t)b * TT + qtok0 + wq * 64 + r32;
;     bf16x8 qa[DK / 16], qb[DK / 16];
; #pragma unroll
;     for (int i = 0; i < DK / 16; ++i) { qa[i] = *(const bf16x8*)(proj + qrow * INW + qcol + i * 16 + hi * 8); qb[i] = *(const bf16x8*)(proj + (qrow + 32) * INW + qcol + i * 16 + hi * 8); }
;     const int lrow = tid >> 3, lch = tid & 7;
;     const bf16_t* ksrc = proj + ((size_t)b * TT + lrow) * INW + kcol + lch * 8;
;     const bf16_t* vsrc = VT + (size_t)lrow * TT + lch * 8;
;     const int NT = nkeys / AKT;
;     u32x4 kreg0, kreg1, vreg0, vreg1;
;     ...
;     const int kfo = r32 * AK_PITCH + (koff + 8 * hi) * 2, vfo = AK_BYTES + r32 * AV_PITCH + 8 * hi;
;     AT_LOAD(0); AT_STORE(0);
;     __syncthreads();
;     float ma = -1e30f, mb = -1e30f, la = 0.f, lb_ = 0.f;
;     f32x16 oa0, oa1, ob0, ob1;
; #pragma unroll
;     for (int r = 0; r < 16; ++r) { oa0[r] = 0.f; oa1[r] = 0.f; ob0[r] = 0.f; ob1[r] = 0.f; }
;     ...
;         if (it < N_FC) {
;             pg8::Gemm g{(const pg8::bf16_t*)(P.ws + WS_FC), (const pg8::bf16_t*)(P.ws + WS_ZCT), CTX, NBATCH * 256, 512}; OneUnit S{0, it};
;             pg8::EpiBf16<0> E{(pg8::bf16_t*)(P.ws + WS_H) + 768, DM, nullptr, 256, (size_t)TT * DM, 1.0f};
;             pg8::gemm_phase<pg8::EpiBf16<0>, OneUnit, false, true>(lds, g, S, E); __syncthreads(); continue; } it -= N_FC;
;         if (it < N_AC) { attn_unit<32, true>(P, l, lds, it >> 2, it & 3, 0, CTX); continue; } it -= N_AC;
.LBB0_381:
	s_and_b64 vcc, exec, s[10:11]
	s_cbranch_vccz .LBB0_405
	s_add_i32 s8, s37, 0xfffffc50
	s_lshr_b32 s9, s8, 2
	s_lshl_b32 s8, s37, 6
	v_mov_b32_e32 v165, v200
	s_and_b32 s8, s8, 0xc0
	s_lshl_b32 s10, s9, 8
	s_or_b32 s10, s10, s8
	v_ashrrev_i32_e32 v4, 3, v165
	s_mul_i32 s64, s10, 0x900
	s_mul_i32 s10, s9, 0x900
	s_mov_b32 s11, s65
	v_ashrrev_i32_e32 v5, 31, v4
	v_mov_b64_e32 v[0:1], s[56:57]
	s_lshl_b64 s[12:13], s[64:65], 1
	v_readlane_b32 s7, v255, 8
	v_lshl_add_u64 v[2:3], v[4:5], 0, s[10:11]
	s_add_u32 s12, s7, s12
	v_readlane_b32 s7, v255, 9
	v_mad_u64_u32 v[6:7], s[18:19], v2, s23, v[0:1]
	s_addc_u32 s13, s7, s13
	v_mad_i32_i24 v7, v3, s23, v7
	s_lshl_b32 s64, s8, 1
	v_lshlrev_b32_e32 v5, 4, v165
	v_lshl_add_u64 v[2:3], v[6:7], 0, s[64:65]
	v_and_b32_e32 v166, 0x70, v5
	v_mov_b32_e32 v167, v129
	v_lshl_add_u64 v[168:169], v[2:3], 0, v[166:167]
	v_mov_b64_e32 v[2:3], s[12:13]
	v_mad_i64_i32 v[2:3], s[12:13], v4, s27, v[2:3]
	s_mov_b32 s7, 0x58000
	v_lshl_add_u64 v[170:171], v[2:3], 0, v[166:167]
	v_add_co_u32_e32 v2, vcc, s7, v168
	v_ashrrev_i32_e32 v167, 8, v165
	s_nop 0
	v_addc_co_u32_e32 v3, vcc, 0, v169, vcc
	v_and_b32_e32 v174, 0xc0, v165
	v_and_b32_e32 v5, 31, v165
	v_lshlrev_b32_e32 v9, 5, v167
	global_load_dwordx4 v[130:133], v[168:169], off offset:512
	global_load_dwordx4 v[134:137], v[2:3], off offset:512
	global_load_dwordx4 v[138:141], v[170:171], off
	global_load_dwordx4 v[146:149], v[170:171], off offset:128
	v_add_u32_e32 v2, s8, v9
	v_or3_b32 v128, v174, s10, v5
	v_bfe_u32 v8, v165, 5, 1
	v_mad_u64_u32 v[0:1], s[10:11], v128, s23, v[0:1]
	v_ashrrev_i32_e32 v3, 31, v2
	v_lshl_add_u64 v[0:1], v[2:3], 1, v[0:1]
	v_lshlrev_b32_e32 v162, 4, v8
	v_mov_b32_e32 v163, v129
	v_lshl_add_u64 v[0:1], v[0:1], 0, v[162:163]
	s_mov_b32 s7, 0x2c000
	v_add_co_u32_e32 v2, vcc, s7, v0
	s_mov_b64 s[10:11], 0x2c000
	global_load_dwordx4 v[142:145], v[0:1], off
	v_addc_co_u32_e32 v3, vcc, 0, v1, vcc
	v_lshl_add_u64 v[6:7], v[0:1], 0, s[10:11]
	global_load_dwordx4 v[150:153], v[0:1], off offset:32
	global_load_dwordx4 v[154:157], v[6:7], off offset:32
	global_load_dwordx4 v[158:161], v[2:3], off
	s_movk_i32 s7, 0x90
	v_mul_lo_u32 v6, v4, s7
	s_movk_i32 s7, 0x78
	v_and_b32_e32 v3, 63, v165
	v_lshlrev_b32_e32 v164, 3, v8
	v_mul_lo_u32 v7, v4, s7
	v_mul_u32_u24_e32 v176, 0x90, v5
	v_mul_u32_u24_e32 v177, 0x108, v5
	v_add_u32_e32 v5, 0, v6
	v_lshlrev_b32_e32 v175, 2, v3
	v_or_b32_e32 v3, v164, v9
	v_add_u32_e32 v6, v5, v7
	s_movk_i32 s7, 0xff88
	s_waitcnt vmcnt(13)
	v_lshlrev_b32_e32 v178, 1, v3
	v_add_u32_e32 v3, v5, v166
	v_add_u32_e32 v5, v6, v166
	v_mad_u64_u32 v[172:173], s[10:11], v4, s7, v[6:7]
	v_add_u32_e32 v4, 0x4800, v5
	v_add_u32_e32 v5, 0x4880, v5
	v_add_u32_e32 v16, v172, v7
	v_mov_b32_e32 v14, v129
	v_mov_b32_e32 v15, v129
	v_mov_b32_e32 v0, v129
	v_mov_b32_e32 v1, v129
	v_mov_b32_e32 v2, v129
	v_mov_b32_e32 v6, v129
	v_mov_b32_e32 v7, v129
	v_mov_b32_e32 v8, v129
	v_mov_b32_e32 v9, v129
	s_waitcnt vmcnt(7)
	ds_write_b128 v3, v[130:133]
	s_waitcnt vmcnt(6)
	ds_write_b128 v3, v[134:137] offset:9216
	s_waitcnt vmcnt(5)
	ds_write2_b64 v4, v[138:139], v[140:141] offset1:1
	s_waitcnt vmcnt(4)
	ds_write2_b64 v5, v[146:147], v[148:149] offset1:1
	v_mov_b32_e32 v3, v129
	v_mov_b32_e32 v4, v129
	v_mov_b32_e32 v5, v129
	v_mov_b32_e32 v10, v129
	v_mov_b32_e32 v11, v129
	v_mov_b32_e32 v12, v129
	v_mov_b32_e32 v13, v129
	v_add_u32_e32 v173, v16, v166
	v_mov_b64_e32 v[30:31], v[14:15]
	v_mov_b64_e32 v[46:47], v[14:15]
	v_mov_b64_e32 v[62:63], v[14:15]
	s_mov_b32 s12, 0
	v_xor_b32_e32 v163, 0x80, v175
	s_mov_b64 s[10:11], -1
	v_mov_b32_e32 v184, 0
	v_mov_b32_e32 v182, 0xf149f2ca
	v_mov_b32_e32 v183, 0xf149f2ca
	v_mov_b32_e32 v179, 0
	v_mov_b64_e32 v[28:29], v[12:13]
	v_mov_b64_e32 v[26:27], v[10:11]
	v_mov_b64_e32 v[24:25], v[8:9]
	v_mov_b64_e32 v[22:23], v[6:7]
	v_mov_b64_e32 v[20:21], v[4:5]
	v_mov_b64_e32 v[18:19], v[2:3]
	v_mov_b64_e32 v[16:17], v[0:1]
	v_mov_b64_e32 v[44:45], v[12:13]
	v_mov_b64_e32 v[42:43], v[10:11]
	v_mov_b64_e32 v[40:41], v[8:9]
	v_mov_b64_e32 v[38:39], v[6:7]
	v_mov_b64_e32 v[36:37], v[4:5]
	v_mov_b64_e32 v[34:35], v[2:3]
	v_mov_b64_e32 v[32:33], v[0:1]
	v_mov_b64_e32 v[60:61], v[12:13]
	v_mov_b64_e32 v[58:59], v[10:11]
	v_mov_b64_e32 v[56:57], v[8:9]
	v_mov_b64_e32 v[54:55], v[6:7]
	v_mov_b64_e32 v[52:53], v[4:5]
	v_mov_b64_e32 v[50:51], v[2:3]
	v_mov_b64_e32 v[48:49], v[0:1]
	s_waitcnt lgkmcnt(0)
	s_waitcnt vmcnt(0)
	s_barrier
	s_branch .LBB0_384

; #define LAS __attribute__((address_space(3)))
; template <int DK, bool IS_A>
; __device__ __forceinline__ void attn_unit(const Params& P, int l, LAS unsigned char* lds, int b, int grp, int qtok0, int nkeys) {
;     ...
;             const LAS unsigned char* kb = lds + buf * A_BUF + kfo + h * 64 * AK_PITCH;
;             const LAS unsigned char* vb = lds + buf * A_BUF + vfo + h * 128;
;             f32x16 pa[2], pb[2];
; #pragma unroll
;             for (int jj = 0; jj < 2; ++jj)
; #pragma unroll
;                 for (int r = 0; r < 16; ++r) { pa[jj][r] = 0.f; pb[jj][r] = 0.f; }
;             __builtin_amdgcn_s_setprio(1);
; #pragma unroll
;             for (int i = 0; i < DK / 16; ++i)
; #pragma unroll
;                 for (int jj = 0; jj < 2; ++jj) {
;                     const bf16x8 kf = *(const LAS bf16x8*)(kb + jj * 32 * AK_PITCH + i * 32);
;                     pa[jj] = __builtin_amdgcn_mfma_f32_32x32x16_bf16(kf, qa[i], pa[jj], 0, 0, 0);
;                     pb[jj] = __builtin_amdgcn_mfma_f32_32x32x16_bf16(kf, qb[i], pb[jj], 0, 0, 0);
;                 }
;             __builtin_amdgcn_s_setprio(0);
.LBB0_386:
	s_bitcmp1_b32 s12, 0
	s_cselect_b32 s10, 0x8a00, 0
	s_add_i32 s10, s10, 0
	v_add_u32_e32 v64, s10, v176
	v_add_u32_e32 v186, v64, v178
	s_setprio 1
	ds_read_b128 v[64:67], v186
	ds_read_b128 v[188:191], v186 offset:32
	s_waitcnt lgkmcnt(1)
	v_mfma_f32_32x32x16_bf16 v[112:127], v[64:67], v[142:145], 0
	v_mfma_f32_32x32x16_bf16 v[96:111], v[64:67], v[158:161], 0
	ds_read_b128 v[64:67], v186 offset:4608
	s_waitcnt lgkmcnt(1)
	v_mfma_f32_32x32x16_bf16 v[112:127], v[188:191], v[150:153], v[112:127]
	v_mfma_f32_32x32x16_bf16 v[96:111], v[188:191], v[154:157], v[96:111]
	ds_read_b128 v[188:191], v186 offset:4640
	s_waitcnt lgkmcnt(1)
	v_mfma_f32_32x32x16_bf16 v[80:95], v[64:67], v[142:145], 0
	v_mfma_f32_32x32x16_bf16 v[64:79], v[64:67], v[158:161], 0
	s_waitcnt lgkmcnt(0)
	v_mfma_f32_32x32x16_bf16 v[80:95], v[188:191], v[150:153], v[80:95]
	v_mfma_f32_32x32x16_bf16 v[64:79], v[188:191], v[154:157], v[64:79]
	s_setprio 0
	s_nop 9
	v_max_f32_e32 v180, v80, v80
	v_max_f32_e32 v181, v112, v112
	v_max_f32_e32 v180, v181, v180
	v_max3_f32 v181, v81, v114, v82
	v_max3_f32 v180, v180, v113, v115
	v_max3_f32 v181, v181, v116, v84
	v_max3_f32 v180, v180, v83, v117
	v_max3_f32 v181, v181, v118, v86
	v_max3_f32 v180, v180, v85, v119
	v_max3_f32 v181, v181, v120, v88
	v_max3_f32 v180, v180, v87, v121
	v_max3_f32 v181, v181, v122, v90
	v_max3_f32 v180, v180, v89, v123
	v_max3_f32 v181, v181, v124, v92
	v_max3_f32 v180, v180, v91, v125
	v_max3_f32 v181, v181, v126, v94
	v_max3_f32 v180, v180, v93, v127
	v_max3_f32 v180, v180, v95, v181
	ds_bpermute_b32 v181, v163, v180
	s_waitcnt lgkmcnt(0)
	v_max3_f32 v187, v182, v180, v181
	v_cmp_gt_f32_e32 vcc, v187, v182
	s_cbranch_vccz .LBB0_388
	v_sub_f32_e32 v180, v182, v187
	v_exp_f32_e32 v180, v180
	s_nop 0
	v_pk_mul_f32 v[62:63], v[62:63], v[180:181] op_sel_hi:[1,0]
	v_pk_mul_f32 v[60:61], v[60:61], v[180:181] op_sel_hi:[1,0]
	v_pk_mul_f32 v[58:59], v[58:59], v[180:181] op_sel_hi:[1,0]
	v_pk_mul_f32 v[56:57], v[56:57], v[180:181] op_sel_hi:[1,0]
	v_pk_mul_f32 v[54:55], v[54:55], v[180:181] op_sel_hi:[1,0]
	v_pk_mul_f32 v[52:53], v[52:53], v[180:181] op_sel_hi:[1,0]
	v_pk_mul_f32 v[50:51], v[50:51], v[180:181] op_sel_hi:[1,0]
	v_pk_mul_f32 v[48:49], v[48:49], v[180:181] op_sel_hi:[1,0]
	v_pk_mul_f32 v[46:47], v[46:47], v[180:181] op_sel_hi:[1,0]
	v_pk_mul_f32 v[44:45], v[44:45], v[180:181] op_sel_hi:[1,0]
	v_pk_mul_f32 v[42:43], v[42:43], v[180:181] op_sel_hi:[1,0]
	v_pk_mul_f32 v[40:41], v[40:41], v[180:181] op_sel_hi:[1,0]
	v_pk_mul_f32 v[38:39], v[38:39], v[180:181] op_sel_hi:[1,0]
	v_pk_mul_f32 v[36:37], v[36:37], v[180:181] op_sel_hi:[1,0]
	v_pk_mul_f32 v[34:35], v[34:35], v[180:181] op_sel_hi:[1,0]
	v_pk_mul_f32 v[32:33], v[32:33], v[180:181] op_sel_hi:[1,0]
	v_mul_f32_e32 v184, v184, v180
	s_branch .LBB0_389

; #define LAS __attribute__((address_space(3)))
; __device__ __forceinline__ unsigned pk2(float lo, float hi) { f32x2_t v = {lo, hi}; bf16x2_t b = __builtin_convertvector(v, bf16x2_t); return __builtin_bit_cast(unsigned, b); }
; template <int DK, bool IS_A>
; __device__ __forceinline__ void attn_unit(const Params& P, int l, LAS unsigned char* lds, int b, int grp, int qtok0, int nkeys) {
;     ...
;             AT_SOFTMAX(pa, ma, la, oa0, oa1);
;             AT_SOFTMAX(pb, mb, lb_, ob0, ob1);
;     ...
; #pragma unroll
;             for (int ks = 0; ks < 4; ++ks) {
;                 const int o8 = 8 * (ks & 1);
;                 u32x4 w; const f32x16& xa = pa[ks >> 1]; const f32x16& xb = pb[ks >> 1];
;                 w.x = pk2(xa[o8], xa[o8 + 1]); w.y = pk2(xa[o8 + 2], xa[o8 + 3]); w.z = pk2(xa[o8 + 4], xa[o8 + 5]); w.w = pk2(xa[o8 + 6], xa[o8 + 7]);
;                 const bf16x8 pfa = __builtin_bit_cast(bf16x8, w);
;                 w.x = pk2(xb[o8], xb[o8 + 1]); w.y = pk2(xb[o8 + 2], xb[o8 + 3]); w.z = pk2(xb[o8 + 4], xb[o8 + 5]); w.w = pk2(xb[o8 + 6], xb[o8 + 7]);
;                 const bf16x8 pfb = __builtin_bit_cast(bf16x8, w);
;                 const u32x2 a0 = *(const LAS u32x2*)(vb + ks * 32), a1 = *(const LAS u32x2*)(vb + ks * 32 + 16);
;                 const u32x2 c0 = *(const LAS u32x2*)(vb + 32 * AV_PITCH + ks * 32), c1 = *(const LAS u32x2*)(vb + 32 * AV_PITCH + ks * 32 + 16);
;                 const bf16x8 v0 = __builtin_bit_cast(bf16x8, ((u32x4){a0.x, a0.y, a1.x, a1.y})), v1 = __builtin_bit_cast(bf16x8, ((u32x4){c0.x, c0.y, c1.x, c1.y}));
;                 oa0 = __builtin_amdgcn_mfma_f32_32x32x16_bf16(v0, pfa, oa0, 0, 0, 0);
;                 oa1 = __builtin_amdgcn_mfma_f32_32x32x16_bf16(v1, pfa, oa1, 0, 0, 0);
;                 ob0 = __builtin_amdgcn_mfma_f32_32x32x16_bf16(v0, pfb, ob0, 0, 0, 0);
;                 ob1 = __builtin_amdgcn_mfma_f32_32x32x16_bf16(v1, pfb, ob1, 0, 0, 0);
;             }
;         }
;         if (t + 1 < NT) AT_STORE(buf ^ 1);
;         __syncthreads();
.LBB0_398:
	ds_read2_b64 v[186:189], v180 offset0:16 offset1:18
	ds_read2_b64 v[194:197], v181 offset0:48 offset1:50
	v_sub_f32_e32 v112, v112, v182
	v_sub_f32_e32 v113, v113, v182
	v_sub_f32_e32 v114, v114, v182
	v_sub_f32_e32 v115, v115, v182
	v_sub_f32_e32 v116, v116, v182
	v_sub_f32_e32 v117, v117, v182
	v_sub_f32_e32 v118, v118, v182
	v_sub_f32_e32 v119, v119, v182
	v_exp_f32_e32 v112, v112
	v_exp_f32_e32 v113, v113
	v_exp_f32_e32 v114, v114
	v_exp_f32_e32 v115, v115
	v_exp_f32_e32 v116, v116
	v_exp_f32_e32 v117, v117
	v_exp_f32_e32 v118, v118
	v_exp_f32_e32 v119, v119
	v_sub_f32_e32 v96, v96, v183
	v_sub_f32_e32 v97, v97, v183
	v_sub_f32_e32 v98, v98, v183
	v_sub_f32_e32 v99, v99, v183
	v_sub_f32_e32 v100, v100, v183
	v_sub_f32_e32 v101, v101, v183
	v_sub_f32_e32 v102, v102, v183
	v_sub_f32_e32 v103, v103, v183
	v_exp_f32_e32 v96, v96
	v_exp_f32_e32 v97, v97
	v_exp_f32_e32 v98, v98
	v_exp_f32_e32 v99, v99
	v_exp_f32_e32 v100, v100
	v_exp_f32_e32 v101, v101
	v_exp_f32_e32 v102, v102
	v_exp_f32_e32 v103, v103
	v_cvt_pk_bf16_f32 v190, v112, v113
	v_cvt_pk_bf16_f32 v191, v114, v115
	v_cvt_pk_bf16_f32 v192, v116, v117
	v_cvt_pk_bf16_f32 v193, v118, v119
	v_sub_f32_e32 v120, v120, v182
	v_sub_f32_e32 v121, v121, v182
	s_waitcnt lgkmcnt(1)
	v_mfma_f32_32x32x16_bf16 v[48:63], v[186:189], v[190:193], v[48:63]
	v_sub_f32_e32 v122, v122, v182
	v_sub_f32_e32 v123, v123, v182
	v_sub_f32_e32 v124, v124, v182
	v_sub_f32_e32 v125, v125, v182
	v_sub_f32_e32 v126, v126, v182
	v_sub_f32_e32 v127, v127, v182
	v_exp_f32_e32 v120, v120
	s_waitcnt lgkmcnt(0)
	v_mfma_f32_32x32x16_bf16 v[32:47], v[194:197], v[190:193], v[32:47]
	v_cvt_pk_bf16_f32 v190, v96, v97
	v_cvt_pk_bf16_f32 v191, v98, v99
	v_cvt_pk_bf16_f32 v192, v100, v101
	v_cvt_pk_bf16_f32 v193, v102, v103
	v_exp_f32_e32 v121, v121
	v_exp_f32_e32 v122, v122
	v_exp_f32_e32 v123, v123
	v_mfma_f32_32x32x16_bf16 v[16:31], v[186:189], v[190:193], v[16:31]
	ds_read2_b64 v[186:189], v180 offset0:20 offset1:22
	v_exp_f32_e32 v124, v124
	v_exp_f32_e32 v125, v125
	v_exp_f32_e32 v126, v126
	v_exp_f32_e32 v127, v127
	v_sub_f32_e32 v104, v104, v183
	v_sub_f32_e32 v105, v105, v183
	v_mfma_f32_32x32x16_bf16 v[0:15], v[194:197], v[190:193], v[0:15]
	ds_read2_b64 v[194:197], v181 offset0:52 offset1:54
	v_sub_f32_e32 v106, v106, v183
	v_sub_f32_e32 v107, v107, v183
	v_sub_f32_e32 v108, v108, v183
	v_sub_f32_e32 v109, v109, v183
	v_sub_f32_e32 v110, v110, v183
	v_sub_f32_e32 v111, v111, v183
	v_exp_f32_e32 v104, v104
	v_exp_f32_e32 v105, v105
	v_exp_f32_e32 v106, v106
	v_exp_f32_e32 v107, v107
	v_exp_f32_e32 v108, v108
	v_exp_f32_e32 v109, v109
	v_exp_f32_e32 v110, v110
	v_exp_f32_e32 v111, v111
	v_cvt_pk_bf16_f32 v190, v120, v121
	v_cvt_pk_bf16_f32 v191, v122, v123
	v_cvt_pk_bf16_f32 v192, v124, v125
	v_cvt_pk_bf16_f32 v193, v126, v127
	v_sub_f32_e32 v66, v66, v183
	v_exp_f32_e32 v185, v66
	s_waitcnt lgkmcnt(1)
	v_mfma_f32_32x32x16_bf16 v[48:63], v[186:189], v[190:193], v[48:63]
	v_sub_f32_e32 v66, v67, v183
	v_exp_f32_e32 v67, v66
	v_sub_f32_e32 v66, v68, v183
	v_exp_f32_e32 v68, v66
	v_sub_f32_e32 v66, v69, v183
	v_sub_f32_e32 v80, v80, v182
	v_sub_f32_e32 v81, v81, v182
	s_waitcnt lgkmcnt(0)
	v_mfma_f32_32x32x16_bf16 v[32:47], v[194:197], v[190:193], v[32:47]
	v_cvt_pk_bf16_f32 v190, v104, v105
	v_cvt_pk_bf16_f32 v191, v106, v107
	v_cvt_pk_bf16_f32 v192, v108, v109
	v_cvt_pk_bf16_f32 v193, v110, v111
	v_sub_f32_e32 v82, v82, v182
	v_sub_f32_e32 v83, v83, v182
	v_sub_f32_e32 v84, v84, v182
	v_mfma_f32_32x32x16_bf16 v[16:31], v[186:189], v[190:193], v[16:31]
	ds_read2_b64 v[186:189], v180 offset0:24 offset1:26
	v_sub_f32_e32 v85, v85, v182
	v_sub_f32_e32 v86, v86, v182
	v_sub_f32_e32 v87, v87, v182
	v_exp_f32_e32 v69, v66
	v_sub_f32_e32 v66, v70, v183
	v_exp_f32_e32 v80, v80
	v_mfma_f32_32x32x16_bf16 v[0:15], v[194:197], v[190:193], v[0:15]
	ds_read2_b64 v[194:197], v181 offset0:56 offset1:58
	v_exp_f32_e32 v81, v81
	v_exp_f32_e32 v82, v82
	v_exp_f32_e32 v83, v83
	v_exp_f32_e32 v84, v84
	v_exp_f32_e32 v85, v85
	v_exp_f32_e32 v86, v86
	v_exp_f32_e32 v87, v87
	v_sub_f32_e32 v64, v64, v183
	v_sub_f32_e32 v65, v65, v183
	v_exp_f32_e32 v70, v66
	v_sub_f32_e32 v66, v71, v183
	v_exp_f32_e32 v64, v64
	v_exp_f32_e32 v65, v65
	v_exp_f32_e32 v71, v66
	v_cvt_pk_bf16_f32 v190, v80, v81
	v_cvt_pk_bf16_f32 v191, v82, v83
	v_cvt_pk_bf16_f32 v192, v84, v85
	v_cvt_pk_bf16_f32 v193, v86, v87
	v_sub_f32_e32 v88, v88, v182
	v_sub_f32_e32 v89, v89, v182
	s_waitcnt lgkmcnt(1)
	v_mfma_f32_32x32x16_bf16 v[48:63], v[186:189], v[190:193], v[48:63]
	v_sub_f32_e32 v90, v90, v182
	v_sub_f32_e32 v91, v91, v182
	v_sub_f32_e32 v92, v92, v182
	v_sub_f32_e32 v93, v93, v182
	v_sub_f32_e32 v94, v94, v182
	v_sub_f32_e32 v66, v95, v182
	v_exp_f32_e32 v88, v88
	s_waitcnt lgkmcnt(0)
	v_mfma_f32_32x32x16_bf16 v[32:47], v[194:197], v[190:193], v[32:47]
	v_cvt_pk_bf16_f32 v190, v64, v65
	v_cvt_pk_bf16_f32 v191, v185, v67
	v_cvt_pk_bf16_f32 v192, v68, v69
	v_cvt_pk_bf16_f32 v193, v70, v71
	v_exp_f32_e32 v89, v89
	v_exp_f32_e32 v90, v90
	v_exp_f32_e32 v91, v91
	v_mfma_f32_32x32x16_bf16 v[16:31], v[186:189], v[190:193], v[16:31]
	ds_read2_b64 v[186:189], v180 offset0:28 offset1:30
	v_exp_f32_e32 v92, v92
	v_exp_f32_e32 v93, v93
	v_exp_f32_e32 v94, v94
	v_exp_f32_e32 v66, v66
	v_sub_f32_e32 v72, v72, v183
	v_sub_f32_e32 v73, v73, v183
	v_mfma_f32_32x32x16_bf16 v[0:15], v[194:197], v[190:193], v[0:15]
	ds_read2_b64 v[194:197], v181 offset0:60 offset1:62
	v_sub_f32_e32 v74, v74, v183
	v_sub_f32_e32 v75, v75, v183
	v_sub_f32_e32 v76, v76, v183
	v_sub_f32_e32 v77, v77, v183
	v_sub_f32_e32 v78, v78, v183
	v_sub_f32_e32 v79, v79, v183
	v_exp_f32_e32 v72, v72
	v_exp_f32_e32 v73, v73
	v_exp_f32_e32 v74, v74
	v_exp_f32_e32 v75, v75
	v_exp_f32_e32 v76, v76
	v_exp_f32_e32 v77, v77
	v_exp_f32_e32 v78, v78
	v_exp_f32_e32 v79, v79
	v_cvt_pk_bf16_f32 v190, v88, v89
	v_cvt_pk_bf16_f32 v191, v90, v91
	v_cvt_pk_bf16_f32 v192, v92, v93
	v_cvt_pk_bf16_f32 v193, v94, v66
	s_and_b64 vcc, exec, s[38:39]
	s_waitcnt lgkmcnt(1)
	v_mfma_f32_32x32x16_bf16 v[48:63], v[186:189], v[190:193], v[48:63]
	s_waitcnt lgkmcnt(0)
	v_mfma_f32_32x32x16_bf16 v[32:47], v[194:197], v[190:193], v[32:47]
	v_cvt_pk_bf16_f32 v190, v72, v73
	v_cvt_pk_bf16_f32 v191, v74, v75
	v_cvt_pk_bf16_f32 v192, v76, v77
	v_cvt_pk_bf16_f32 v193, v78, v79
	s_nop 1
	v_mfma_f32_32x32x16_bf16 v[16:31], v[186:189], v[190:193], v[16:31]
	v_mfma_f32_32x32x16_bf16 v[0:15], v[194:197], v[190:193], v[0:15]
	s_cbranch_vccnz .LBB0_383
	s_waitcnt vmcnt(0)
	v_add_u32_e32 v95, v172, v166
	ds_write_b128 v95, v[130:133] offset:35328
	ds_write_b128 v95, v[134:137] offset:44544
	v_add_u32_e32 v95, 0xd200, v173
	ds_write2_b64 v95, v[138:139], v[140:141] offset1:1
	v_add_u32_e32 v95, 0xd280, v173
	ds_write2_b64 v95, v[146:147], v[148:149] offset1:1
	s_branch .LBB0_383

; #define LAS __attribute__((address_space(3)))
; __device__ __forceinline__ int opaque_tid() { int t = threadIdx.x; asm volatile("" : "+v"(t)); return t; }
; #define AT_LOAD(t_) do { const bf16_t* kn = ksrc + (size_t)(t_) * AKT * INW; const bf16_t* vn = vsrc + (t_) * AKT; \
;         kreg0 = *(const u32x4*)kn; kreg1 = *(const u32x4*)(kn + (size_t)64 * INW); vreg0 = *(const u32x4*)vn; vreg1 = *(const u32x4*)(vn + 64); } while (0)
; template <int DK, bool IS_A>
; __device__ __forceinline__ void attn_unit(const Params& P, int l, LAS unsigned char* lds, int b, int grp, int qtok0, int nkeys) {
;     const int tid = opaque_tid(), lane = tid & 63, wave = tid >> 6, s = wave >> 2, wq = wave & 3, r32 = lane & 31, hi = lane >> 5;
;     const bf16_t* proj = (const bf16_t*)(P.ws + WS_PROJ);
;     bf16_t* mix = (bf16_t*)(P.ws + WS_H);
;     const int qcol = IS_A ? PA_Q + grp * 64 + s * 32 : PC_Q + (2 * grp + s) * 64;
;     const int kcol = IS_A ? PA_K + grp * 64 : PC_K + grp * 64;
;     const int koff = IS_A ? s * 32 : 0;
;     const bf16_t* VT = IS_A ? (const bf16_t*)(P.ws + WS_VTA) + ((size_t)(b * 4 + grp) * 64) * TT : (const bf16_t*)(P.ws + WS_VTC) + ((size_t)(b * 2 + grp) * 64) * TT;
;     const size_t qrow = (size_t)b * TT + qtok0 + wq * 64 + r32;
;     bf16x8 qa[DK / 16], qb[DK / 16];
; #pragma unroll
;     for (int i = 0; i < DK / 16; ++i) { qa[i] = *(const bf16x8*)(proj + qrow * INW + qcol + i * 16 + hi * 8); qb[i] = *(const bf16x8*)(proj + (qrow + 32) * INW + qcol + i * 16 + hi * 8); }
;     const int lrow = tid >> 3, lch = tid & 7;
;     const bf16_t* ksrc = proj + ((size_t)b * TT + lrow) * INW + kcol + lch * 8;
;     const bf16_t* vsrc = VT + (size_t)lrow * TT + lch * 8;
;     const int NT = nkeys / AKT;
;     u32x4 kreg0, kreg1, vreg0, vreg1;
;     ...
;     const int kfo = r32 * AK_PITCH + (koff + 8 * hi) * 2, vfo = AK_BYTES + r32 * AV_PITCH + 8 * hi;
;     AT_LOAD(0); AT_STORE(0);
;     __syncthreads();
;     float ma = -1e30f, mb = -1e30f, la = 0.f, lb_ = 0.f;
;     f32x16 oa0, oa1, ob0, ob1;
; #pragma unroll
;     for (int r = 0; r < 16; ++r) { oa0[r] = 0.f; oa1[r] = 0.f; ob0[r] = 0.f; ob1[r] = 0.f; }
;     ...
;         if (it < N_A) { attn_unit<32, true>(P, l, lds, it >> 5, (it >> 3) & 3, CTX + (it & 7) * 256, TT); continue; } it -= N_A;
.LBB0_415:
	s_andn2_b64 vcc, exec, s[10:11]
	s_cbranch_vccnz .LBB0_439
	s_add_i32 s8, s37, 0xfffffe60
	s_lshr_b32 s15, s8, 5
	s_lshl_b32 s8, s37, 8
	s_and_b32 s8, s8, 0x700
	s_mul_i32 s10, s15, 0x900
	s_add_i32 s9, s8, s10
	s_lshl_b32 s8, s37, 3
	v_mov_b32_e32 v165, v200
	s_and_b32 s8, s8, 0xc0
	s_lshl_b32 s11, s15, 8
	s_or_b32 s11, s11, s8
	v_ashrrev_i32_e32 v2, 3, v165
	s_mul_i32 s64, s11, 0x900
	s_mov_b32 s11, s65
	v_ashrrev_i32_e32 v3, 31, v2
	s_addk_i32 s9, 0x100
	v_mov_b64_e32 v[0:1], s[56:57]
	s_lshl_b64 s[12:13], s[64:65], 1
	v_readlane_b32 s7, v255, 8
	v_lshl_add_u64 v[4:5], v[2:3], 0, s[10:11]
	s_add_u32 s12, s7, s12
	v_readlane_b32 s7, v255, 9
	v_mad_u64_u32 v[6:7], s[10:11], v4, s23, v[0:1]
	s_addc_u32 s13, s7, s13
	v_mad_i32_i24 v7, v5, s23, v7
	s_lshl_b32 s64, s8, 1
	v_lshlrev_b32_e32 v3, 4, v165
	v_lshl_add_u64 v[6:7], v[6:7], 0, s[64:65]
	v_and_b32_e32 v166, 0x70, v3
	v_mov_b32_e32 v167, v129
	v_lshl_add_u64 v[6:7], v[6:7], 0, v[166:167]
	s_mov_b32 s7, 0x58000
	v_mov_b64_e32 v[8:9], s[12:13]
	global_load_dwordx4 v[130:133], v[6:7], off offset:512
	v_add_co_u32_e32 v6, vcc, s7, v6
	v_mad_i64_i32 v[8:9], s[10:11], v2, s27, v[8:9]
	s_nop 0
	v_addc_co_u32_e32 v7, vcc, 0, v7, vcc
	v_lshl_add_u64 v[8:9], v[8:9], 0, v[166:167]
	global_load_dwordx4 v[134:137], v[6:7], off offset:512
	global_load_dwordx4 v[154:157], v[8:9], off
	global_load_dwordx4 v[158:161], v[8:9], off offset:128
	v_ashrrev_i32_e32 v172, 8, v165
	v_and_b32_e32 v173, 0xc0, v165
	v_and_b32_e32 v3, 31, v165
	v_lshlrev_b32_e32 v11, 5, v172
	v_add_u32_e32 v6, s8, v11
	v_or3_b32 v128, s9, v173, v3
	v_bfe_u32 v10, v165, 5, 1
	v_mad_u64_u32 v[0:1], s[10:11], v128, s23, v[0:1]
	v_ashrrev_i32_e32 v7, 31, v6
	v_lshl_add_u64 v[0:1], v[6:7], 1, v[0:1]
	v_lshlrev_b32_e32 v162, 4, v10
	v_mov_b32_e32 v163, v129
	v_lshl_add_u64 v[0:1], v[0:1], 0, v[162:163]
	s_mov_b32 s7, 0x2c000
	s_mov_b64 s[10:11], 0x2c000
	v_add_co_u32_e32 v8, vcc, s7, v0
	v_lshl_add_u64 v[6:7], v[0:1], 0, s[10:11]
	s_nop 0
	v_addc_co_u32_e32 v9, vcc, 0, v1, vcc
	global_load_dwordx4 v[138:141], v[0:1], off
	global_load_dwordx4 v[142:145], v[0:1], off offset:32
	global_load_dwordx4 v[146:149], v[8:9], off
	global_load_dwordx4 v[150:153], v[6:7], off offset:32
	s_movk_i32 s7, 0x90
	v_and_b32_e32 v0, 63, v165
	v_lshlrev_b32_e32 v164, 3, v10
	v_mul_lo_u32 v175, v2, s7
	s_movk_i32 s7, 0x108
	v_mul_lo_u32 v176, v2, s7
	v_lshlrev_b32_e32 v174, 2, v0
	v_or_b32_e32 v1, v164, v11
	v_add3_u32 v0, 0, v175, v166
	s_movk_i32 s7, 0x78
	v_mad_u64_u32 v[6:7], s[10:11], v2, s7, v[0:1]
	s_bfe_u32 s13, s37, 0x20003
	s_mul_i32 s12, s15, 0x90000
	s_mul_i32 s10, s13, 0x24000
	s_add_i32 s64, s12, s10
	s_lshl_b64 s[10:11], s[64:65], 1
	s_add_u32 s10, s54, s10
	v_lshlrev_b32_e32 v179, 1, v1
	v_add_u32_e32 v1, 0x4800, v6
	s_addc_u32 s11, s55, s11
	v_mul_u32_u24_e32 v177, 0x90, v3
	s_waitcnt vmcnt(13)
	v_mul_u32_u24_e32 v178, 0x108, v3
	v_add_u32_e32 v3, 0x4880, v6
	v_mov_b32_e32 v14, v129
	v_mov_b32_e32 v15, v129
	v_mov_b32_e32 v6, v129
	v_mov_b32_e32 v7, v129
	s_waitcnt vmcnt(7)
	ds_write_b128 v0, v[130:133]
	s_waitcnt vmcnt(6)
	ds_write_b128 v0, v[134:137] offset:9216
	s_waitcnt vmcnt(5)
	ds_write2_b64 v1, v[154:155], v[156:157] offset1:1
	s_waitcnt vmcnt(4)
	ds_write2_b64 v3, v[158:159], v[160:161] offset1:1
	v_mov_b64_e32 v[0:1], s[10:11]
	v_mad_i64_i32 v[168:169], s[10:11], v2, s27, v[0:1]
	s_lshl_b32 s10, s13, 7
	s_add_u32 s10, s54, s10
	s_addc_u32 s11, s55, 0
	v_mov_b64_e32 v[0:1], s[10:11]
	v_mad_u64_u32 v[170:171], s[10:11], v4, s23, v[0:1]
	v_mad_i32_i24 v171, v5, s23, v171
	v_mov_b32_e32 v0, v129
	v_mov_b32_e32 v1, v129
	v_mov_b32_e32 v2, v129
	v_mov_b32_e32 v3, v129
	v_mov_b32_e32 v4, v129
	v_mov_b32_e32 v5, v129
	v_mov_b32_e32 v8, v129
	v_mov_b32_e32 v9, v129
	v_mov_b32_e32 v10, v129
	v_mov_b32_e32 v11, v129
	v_mov_b32_e32 v12, v129
	v_mov_b32_e32 v13, v129
	v_mov_b64_e32 v[30:31], v[14:15]
	v_mov_b64_e32 v[46:47], v[14:15]
	v_mov_b64_e32 v[62:63], v[14:15]
	s_mov_b32 s9, 0
	v_xor_b32_e32 v163, 0x80, v174
	v_mov_b32_e32 v185, 0
	v_mov_b32_e32 v181, 0xf149f2ca
	v_mov_b32_e32 v184, 0xf149f2ca
	v_mov_b32_e32 v180, 0
	v_mov_b64_e32 v[28:29], v[12:13]
	v_mov_b64_e32 v[26:27], v[10:11]
	v_mov_b64_e32 v[24:25], v[8:9]
	v_mov_b64_e32 v[22:23], v[6:7]
	v_mov_b64_e32 v[20:21], v[4:5]
	v_mov_b64_e32 v[18:19], v[2:3]
	v_mov_b64_e32 v[16:17], v[0:1]
	v_mov_b64_e32 v[44:45], v[12:13]
	v_mov_b64_e32 v[42:43], v[10:11]
	v_mov_b64_e32 v[40:41], v[8:9]
	v_mov_b64_e32 v[38:39], v[6:7]
	v_mov_b64_e32 v[36:37], v[4:5]
	v_mov_b64_e32 v[34:35], v[2:3]
	v_mov_b64_e32 v[32:33], v[0:1]
	v_mov_b64_e32 v[60:61], v[12:13]
	v_mov_b64_e32 v[58:59], v[10:11]
	v_mov_b64_e32 v[56:57], v[8:9]
	v_mov_b64_e32 v[54:55], v[6:7]
	v_mov_b64_e32 v[52:53], v[4:5]
	v_mov_b64_e32 v[50:51], v[2:3]
	v_mov_b64_e32 v[48:49], v[0:1]
	s_waitcnt lgkmcnt(0)
	s_waitcnt vmcnt(0)
	s_mov_b32 s100, 0
	v_readfirstlane_b32 s101, v200
	s_nop 3
	s_lshr_b32 s101, s101, 8
	s_barrier
	s_branch .LBB0_418
; template <int DK, bool IS_A>
; __device__ __forceinline__ void attn_unit(const Params& P, int l, LAS unsigned char* lds, int b, int grp, int qtok0, int nkeys) {
;     ...
;         if (t + 1 < NT) AT_STORE(buf ^ 1);
;         __syncthreads();
;     }
.LBB0_417:
	v_add_f32_e32 v95, 0, v96
	v_add_f32_e32 v95, v97, v95
	v_add_f32_e32 v95, v98, v95
	v_add_f32_e32 v95, v99, v95
	v_add_f32_e32 v95, v100, v95
	v_add_f32_e32 v95, v101, v95
	v_add_f32_e32 v95, v102, v95
	v_add_f32_e32 v95, v103, v95
	v_add_f32_e32 v95, v104, v95
	v_add_f32_e32 v95, v105, v95
	v_add_f32_e32 v95, v106, v95
	v_add_f32_e32 v95, v107, v95
	v_add_f32_e32 v95, v108, v95
	v_add_f32_e32 v95, v109, v95
	v_add_f32_e32 v95, v110, v95
	v_add_f32_e32 v95, v111, v95
	v_add_f32_e32 v64, v64, v95
	v_add_f32_e32 v64, v65, v64
	v_add_f32_e32 v64, v186, v64
	v_add_f32_e32 v64, v67, v64
	v_add_f32_e32 v64, v68, v64
	v_add_f32_e32 v64, v69, v64
	v_add_f32_e32 v64, v70, v64
	v_add_f32_e32 v64, v71, v64
	v_add_f32_e32 v64, v72, v64
	v_add_f32_e32 v64, v73, v64
	v_add_f32_e32 v64, v74, v64
	v_add_f32_e32 v64, v75, v64
	v_add_f32_e32 v64, v76, v64
	v_add_f32_e32 v64, v77, v64
	v_add_f32_e32 v64, v78, v64
	v_add_f32_e32 v64, v79, v64
	v_add_f32_e32 v180, v180, v64
	v_add_f32_e32 v64, 0, v112
	v_add_f32_e32 v64, v113, v64
	v_add_f32_e32 v64, v114, v64
	v_add_f32_e32 v64, v115, v64
	v_add_f32_e32 v64, v116, v64
	v_add_f32_e32 v64, v117, v64
	v_add_f32_e32 v64, v118, v64
	v_add_f32_e32 v64, v119, v64
	v_add_f32_e32 v64, v120, v64
	v_add_f32_e32 v64, v121, v64
	v_add_f32_e32 v64, v122, v64
	v_add_f32_e32 v64, v123, v64
	v_add_f32_e32 v64, v124, v64
	v_add_f32_e32 v64, v125, v64
	v_add_f32_e32 v64, v126, v64
	v_add_f32_e32 v64, v127, v64
	v_add_f32_e32 v64, v80, v64
	v_add_f32_e32 v64, v81, v64
	v_add_f32_e32 v64, v82, v64
	v_add_f32_e32 v64, v83, v64
	v_add_f32_e32 v64, v84, v64
	v_add_f32_e32 v64, v85, v64
	v_add_f32_e32 v64, v86, v64
	v_add_f32_e32 v64, v87, v64
	v_add_f32_e32 v64, v88, v64
	v_add_f32_e32 v64, v89, v64
	v_add_f32_e32 v64, v90, v64
	v_add_f32_e32 v64, v91, v64
	v_add_f32_e32 v64, v92, v64
	v_add_f32_e32 v64, v93, v64
	v_add_f32_e32 v64, v94, v64
	s_mov_b64 s[10:11], 0x100
	v_add_f32_e32 v64, v66, v64
	s_add_i32 s9, s9, 1
	v_lshl_add_u64 v[168:169], v[168:169], 0, s[10:11]
	s_mov_b64 s[10:11], 0xb0000
	v_add_f32_e32 v185, v185, v64
	v_lshl_add_u64 v[170:171], v[170:171], 0, s[10:11]
	s_waitcnt lgkmcnt(0)
	s_cmp_lg_u32 s101, 0
	s_cbranch_scc1 .Latta_nobar
	s_barrier
.Latta_nobar:
	s_add_u32 s100, s100, 0x8a00
	s_cmp_eq_u32 s100, 0x19e00
	s_cselect_b32 s100, 0, s100
	s_cmp_eq_u32 s9, 18
	s_cbranch_scc1 .LBB0_434

; #define LAS __attribute__((address_space(3)))
; template <int DK, bool IS_A>
; __device__ __forceinline__ void attn_unit(const Params& P, int l, LAS unsigned char* lds, int b, int grp, int qtok0, int nkeys) {
;     ...
;             const LAS unsigned char* kb = lds + buf * A_BUF + kfo + h * 64 * AK_PITCH;
;             const LAS unsigned char* vb = lds + buf * A_BUF + vfo + h * 128;
;             f32x16 pa[2], pb[2];
; #pragma unroll
;             for (int jj = 0; jj < 2; ++jj)
; #pragma unroll
;                 for (int r = 0; r < 16; ++r) { pa[jj][r] = 0.f; pb[jj][r] = 0.f; }
;             __builtin_amdgcn_s_setprio(1);
; #pragma unroll
;             for (int i = 0; i < DK / 16; ++i)
; #pragma unroll
;                 for (int jj = 0; jj < 2; ++jj) {
;                     const bf16x8 kf = *(const LAS bf16x8*)(kb + jj * 32 * AK_PITCH + i * 32);
;                     pa[jj] = __builtin_amdgcn_mfma_f32_32x32x16_bf16(kf, qa[i], pa[jj], 0, 0, 0);
;                     pb[jj] = __builtin_amdgcn_mfma_f32_32x32x16_bf16(kf, qb[i], pb[jj], 0, 0, 0);
;                 }
;             __builtin_amdgcn_s_setprio(0);
.LBB0_420:
	s_mov_b32 s12, s100
	v_add_u32_e32 v64, s12, v177
	v_add_u32_e32 v187, v64, v179
	s_setprio 1
	ds_read_b128 v[64:67], v187
	ds_read_b128 v[188:191], v187 offset:32
	s_waitcnt lgkmcnt(1)
	v_mfma_f32_32x32x16_bf16 v[112:127], v[64:67], v[138:141], 0
	v_mfma_f32_32x32x16_bf16 v[96:111], v[64:67], v[146:149], 0
	ds_read_b128 v[64:67], v187 offset:4608
	s_waitcnt lgkmcnt(1)
	v_mfma_f32_32x32x16_bf16 v[112:127], v[188:191], v[142:145], v[112:127]
	v_mfma_f32_32x32x16_bf16 v[96:111], v[188:191], v[150:153], v[96:111]
	ds_read_b128 v[188:191], v187 offset:4640
	s_waitcnt lgkmcnt(1)
	v_mfma_f32_32x32x16_bf16 v[80:95], v[64:67], v[138:141], 0
	v_mfma_f32_32x32x16_bf16 v[64:79], v[64:67], v[146:149], 0
	s_waitcnt lgkmcnt(0)
	v_mfma_f32_32x32x16_bf16 v[80:95], v[188:191], v[142:145], v[80:95]
	v_mfma_f32_32x32x16_bf16 v[64:79], v[188:191], v[150:153], v[64:79]
	s_setprio 0
	s_nop 9
	v_max_f32_e32 v182, v80, v80
	v_max_f32_e32 v183, v112, v112
	v_max_f32_e32 v182, v183, v182
	v_max3_f32 v183, v81, v114, v82
	v_max3_f32 v182, v182, v113, v115
	v_max3_f32 v183, v183, v116, v84
	v_max3_f32 v182, v182, v83, v117
	v_max3_f32 v183, v183, v118, v86
	v_max3_f32 v182, v182, v85, v119
	v_max3_f32 v183, v183, v120, v88
	v_max3_f32 v182, v182, v87, v121
	v_max3_f32 v183, v183, v122, v90
	v_max3_f32 v182, v182, v89, v123
	v_max3_f32 v183, v183, v124, v92
	v_max3_f32 v182, v182, v91, v125
	v_max3_f32 v183, v183, v126, v94
	v_max3_f32 v182, v182, v93, v127
	v_max3_f32 v182, v182, v95, v183
	ds_bpermute_b32 v183, v163, v182
	s_waitcnt lgkmcnt(0)
	v_max3_f32 v188, v181, v182, v183
	v_cmp_gt_f32_e32 vcc, v188, v181
	s_cbranch_vccz .LBB0_422
	v_sub_f32_e32 v181, v181, v188
	v_exp_f32_e32 v182, v181
	s_nop 0
	v_pk_mul_f32 v[62:63], v[62:63], v[182:183] op_sel_hi:[1,0]
	v_pk_mul_f32 v[60:61], v[60:61], v[182:183] op_sel_hi:[1,0]
	v_pk_mul_f32 v[58:59], v[58:59], v[182:183] op_sel_hi:[1,0]
	v_pk_mul_f32 v[56:57], v[56:57], v[182:183] op_sel_hi:[1,0]
	v_pk_mul_f32 v[54:55], v[54:55], v[182:183] op_sel_hi:[1,0]
	v_pk_mul_f32 v[52:53], v[52:53], v[182:183] op_sel_hi:[1,0]
	v_pk_mul_f32 v[50:51], v[50:51], v[182:183] op_sel_hi:[1,0]
	v_pk_mul_f32 v[48:49], v[48:49], v[182:183] op_sel_hi:[1,0]
	v_pk_mul_f32 v[46:47], v[46:47], v[182:183] op_sel_hi:[1,0]
	v_pk_mul_f32 v[44:45], v[44:45], v[182:183] op_sel_hi:[1,0]
	v_pk_mul_f32 v[42:43], v[42:43], v[182:183] op_sel_hi:[1,0]
	v_pk_mul_f32 v[40:41], v[40:41], v[182:183] op_sel_hi:[1,0]
	v_pk_mul_f32 v[38:39], v[38:39], v[182:183] op_sel_hi:[1,0]
	v_pk_mul_f32 v[36:37], v[36:37], v[182:183] op_sel_hi:[1,0]
	v_pk_mul_f32 v[34:35], v[34:35], v[182:183] op_sel_hi:[1,0]
	v_pk_mul_f32 v[32:33], v[32:33], v[182:183] op_sel_hi:[1,0]
	v_mul_f32_e32 v185, v185, v182
	s_branch .LBB0_423

; template <int DK, bool IS_A>
; __device__ __forceinline__ void attn_unit(const Params& P, int l, LAS unsigned char* lds, int b, int grp, int qtok0, int nkeys) {
;     ...
;         if (t + 1 < NT) AT_STORE(buf ^ 1);
;         __syncthreads();
.LBB0_432:
	s_cmp_eq_u32 s101, 0
	s_cbranch_scc1 .Latta_w03
	s_cmp_eq_u64 s[10:11], 0
	s_cbranch_scc1 .Latta_pubdone
	s_add_u32 vcc_lo, s100, 0x8a00
	s_cmp_eq_u32 vcc_lo, 0x19e00
	s_cselect_b32 vcc_lo, 0, vcc_lo
	s_waitcnt vmcnt(0)
	v_add3_u32 v216, vcc_lo, v175, v166
	v_add3_u32 v217, vcc_lo, v176, v166
	v_add_u32_e32 v218, 0x4800, v217
	ds_write_b128 v216, v[130:133]
	ds_write_b128 v216, v[134:137] offset:9216
	ds_write2_b64 v218, v[154:155], v[156:157] offset1:1
	v_add_u32_e32 v216, 0x4880, v217
	ds_write2_b64 v216, v[158:159], v[160:161] offset1:1
.Latta_pubdone:
	s_waitcnt lgkmcnt(0)
	s_barrier
; #define LAS __attribute__((address_space(3)))
; __device__ __forceinline__ unsigned pk2(float lo, float hi) { f32x2_t v = {lo, hi}; bf16x2_t b = __builtin_convertvector(v, bf16x2_t); return __builtin_bit_cast(unsigned, b); }
; template <int DK, bool IS_A>
; __device__ __forceinline__ void attn_unit(const Params& P, int l, LAS unsigned char* lds, int b, int grp, int qtok0, int nkeys) {
;     ...
; #pragma unroll
;             for (int ks = 0; ks < 4; ++ks) {
;                 const int o8 = 8 * (ks & 1);
;                 u32x4 w; const f32x16& xa = pa[ks >> 1]; const f32x16& xb = pb[ks >> 1];
;                 w.x = pk2(xa[o8], xa[o8 + 1]); w.y = pk2(xa[o8 + 2], xa[o8 + 3]); w.z = pk2(xa[o8 + 4], xa[o8 + 5]); w.w = pk2(xa[o8 + 6], xa[o8 + 7]);
;                 const bf16x8 pfa = __builtin_bit_cast(bf16x8, w);
;                 w.x = pk2(xb[o8], xb[o8 + 1]); w.y = pk2(xb[o8 + 2], xb[o8 + 3]); w.z = pk2(xb[o8 + 4], xb[o8 + 5]); w.w = pk2(xb[o8 + 6], xb[o8 + 7]);
;                 const bf16x8 pfb = __builtin_bit_cast(bf16x8, w);
;                 const u32x2 a0 = *(const LAS u32x2*)(vb + ks * 32), a1 = *(const LAS u32x2*)(vb + ks * 32 + 16);
;                 const u32x2 c0 = *(const LAS u32x2*)(vb + 32 * AV_PITCH + ks * 32), c1 = *(const LAS u32x2*)(vb + 32 * AV_PITCH + ks * 32 + 16);
;                 const bf16x8 v0 = __builtin_bit_cast(bf16x8, ((u32x4){a0.x, a0.y, a1.x, a1.y})), v1 = __builtin_bit_cast(bf16x8, ((u32x4){c0.x, c0.y, c1.x, c1.y}));
;                 oa0 = __builtin_amdgcn_mfma_f32_32x32x16_bf16(v0, pfa, oa0, 0, 0, 0);
;                 oa1 = __builtin_amdgcn_mfma_f32_32x32x16_bf16(v1, pfa, oa1, 0, 0, 0);
;                 ob0 = __builtin_amdgcn_mfma_f32_32x32x16_bf16(v0, pfb, ob0, 0, 0, 0);
;                 ob1 = __builtin_amdgcn_mfma_f32_32x32x16_bf16(v1, pfb, ob1, 0, 0, 0);
;             }
;         }
;         if (t + 1 < NT) AT_STORE(buf ^ 1);
.Latta_w03:
	ds_read2_b64 v[186:189], v182 offset0:16 offset1:18
	ds_read2_b64 v[194:197], v183 offset0:48 offset1:50
	v_sub_f32_e32 v112, v112, v181
	v_sub_f32_e32 v113, v113, v181
	v_sub_f32_e32 v114, v114, v181
	v_sub_f32_e32 v115, v115, v181
	v_sub_f32_e32 v116, v116, v181
	v_sub_f32_e32 v117, v117, v181
	v_sub_f32_e32 v118, v118, v181
	v_sub_f32_e32 v119, v119, v181
	v_exp_f32_e32 v112, v112
	v_exp_f32_e32 v113, v113
	v_exp_f32_e32 v114, v114
	v_exp_f32_e32 v115, v115
	v_exp_f32_e32 v116, v116
	v_exp_f32_e32 v117, v117
	v_exp_f32_e32 v118, v118
	v_exp_f32_e32 v119, v119
	v_sub_f32_e32 v96, v96, v184
	v_sub_f32_e32 v97, v97, v184
	v_sub_f32_e32 v98, v98, v184
	v_sub_f32_e32 v99, v99, v184
	v_sub_f32_e32 v100, v100, v184
	v_sub_f32_e32 v101, v101, v184
	v_sub_f32_e32 v102, v102, v184
	v_sub_f32_e32 v103, v103, v184
	v_exp_f32_e32 v96, v96
	v_exp_f32_e32 v97, v97
	v_exp_f32_e32 v98, v98
	v_exp_f32_e32 v99, v99
	v_exp_f32_e32 v100, v100
	v_exp_f32_e32 v101, v101
	v_exp_f32_e32 v102, v102
	v_exp_f32_e32 v103, v103
	v_cvt_pk_bf16_f32 v190, v112, v113
	v_cvt_pk_bf16_f32 v191, v114, v115
	v_cvt_pk_bf16_f32 v192, v116, v117
	v_cvt_pk_bf16_f32 v193, v118, v119
	v_sub_f32_e32 v120, v120, v181
	v_sub_f32_e32 v121, v121, v181
	s_waitcnt lgkmcnt(1)
	v_mfma_f32_32x32x16_bf16 v[48:63], v[186:189], v[190:193], v[48:63]
	v_sub_f32_e32 v122, v122, v181
	v_sub_f32_e32 v123, v123, v181
	v_sub_f32_e32 v124, v124, v181
	v_sub_f32_e32 v125, v125, v181
	v_sub_f32_e32 v126, v126, v181
	v_sub_f32_e32 v127, v127, v181
	v_exp_f32_e32 v120, v120
	s_waitcnt lgkmcnt(0)
	v_mfma_f32_32x32x16_bf16 v[32:47], v[194:197], v[190:193], v[32:47]
	v_cvt_pk_bf16_f32 v190, v96, v97
	v_cvt_pk_bf16_f32 v191, v98, v99
	v_cvt_pk_bf16_f32 v192, v100, v101
	v_cvt_pk_bf16_f32 v193, v102, v103
	v_exp_f32_e32 v121, v121
	v_exp_f32_e32 v122, v122
	v_exp_f32_e32 v123, v123
	v_mfma_f32_32x32x16_bf16 v[16:31], v[186:189], v[190:193], v[16:31]
	ds_read2_b64 v[186:189], v182 offset0:20 offset1:22
	v_exp_f32_e32 v124, v124
	v_exp_f32_e32 v125, v125
	v_exp_f32_e32 v126, v126
	v_exp_f32_e32 v127, v127
	v_sub_f32_e32 v104, v104, v184
	v_sub_f32_e32 v105, v105, v184
	v_mfma_f32_32x32x16_bf16 v[0:15], v[194:197], v[190:193], v[0:15]
	ds_read2_b64 v[194:197], v183 offset0:52 offset1:54
	v_sub_f32_e32 v106, v106, v184
	v_sub_f32_e32 v107, v107, v184
	v_sub_f32_e32 v108, v108, v184
	v_sub_f32_e32 v109, v109, v184
	v_sub_f32_e32 v110, v110, v184
	v_sub_f32_e32 v111, v111, v184
	v_exp_f32_e32 v104, v104
	v_exp_f32_e32 v105, v105
	v_exp_f32_e32 v106, v106
	v_exp_f32_e32 v107, v107
	v_exp_f32_e32 v108, v108
	v_exp_f32_e32 v109, v109
	v_exp_f32_e32 v110, v110
	v_exp_f32_e32 v111, v111
	v_cvt_pk_bf16_f32 v190, v120, v121
	v_cvt_pk_bf16_f32 v191, v122, v123
	v_cvt_pk_bf16_f32 v192, v124, v125
	v_cvt_pk_bf16_f32 v193, v126, v127
	v_sub_f32_e32 v66, v66, v184
	ds_read2_b64 v[204:207], v182 offset0:24 offset1:26
	s_waitcnt lgkmcnt(2)
	v_mfma_f32_32x32x16_bf16 v[48:63], v[186:189], v[190:193], v[48:63]
	v_sub_f32_e32 v80, v80, v181
	v_sub_f32_e32 v81, v81, v181
	v_sub_f32_e32 v82, v82, v181
	v_sub_f32_e32 v83, v83, v181
	v_sub_f32_e32 v84, v84, v181
	v_sub_f32_e32 v85, v85, v181
	v_sub_f32_e32 v86, v86, v181
	s_waitcnt lgkmcnt(1)
	v_mfma_f32_32x32x16_bf16 v[32:47], v[194:197], v[190:193], v[32:47]
	v_cvt_pk_bf16_f32 v190, v104, v105
	v_cvt_pk_bf16_f32 v191, v106, v107
	v_cvt_pk_bf16_f32 v192, v108, v109
	v_cvt_pk_bf16_f32 v193, v110, v111
	v_sub_f32_e32 v87, v87, v181
	v_exp_f32_e32 v80, v80
	v_exp_f32_e32 v81, v81
	v_mfma_f32_32x32x16_bf16 v[16:31], v[186:189], v[190:193], v[16:31]
	v_exp_f32_e32 v186, v66
	v_sub_f32_e32 v66, v67, v184
	v_exp_f32_e32 v67, v66
	v_sub_f32_e32 v66, v68, v184
	v_exp_f32_e32 v68, v66
	v_sub_f32_e32 v66, v69, v184
	v_exp_f32_e32 v69, v66
	v_mfma_f32_32x32x16_bf16 v[0:15], v[194:197], v[190:193], v[0:15]
	ds_read2_b64 v[192:195], v183 offset0:56 offset1:58
	v_sub_f32_e32 v66, v70, v184
	v_exp_f32_e32 v82, v82
	v_exp_f32_e32 v83, v83
	v_exp_f32_e32 v84, v84
	v_exp_f32_e32 v85, v85
	v_exp_f32_e32 v86, v86
	v_exp_f32_e32 v87, v87
	v_sub_f32_e32 v64, v64, v184
	v_sub_f32_e32 v65, v65, v184
	v_exp_f32_e32 v70, v66
	v_sub_f32_e32 v66, v71, v184
	v_exp_f32_e32 v64, v64
	v_exp_f32_e32 v65, v65
	v_exp_f32_e32 v71, v66
	v_cvt_pk_bf16_f32 v188, v80, v81
	v_cvt_pk_bf16_f32 v189, v82, v83
	v_cvt_pk_bf16_f32 v190, v84, v85
	v_cvt_pk_bf16_f32 v191, v86, v87
	ds_read2_b64 v[196:199], v182 offset0:28 offset1:30
	v_sub_f32_e32 v88, v88, v181
	s_waitcnt lgkmcnt(2)
	v_mfma_f32_32x32x16_bf16 v[48:63], v[204:207], v[188:191], v[48:63]
	v_sub_f32_e32 v89, v89, v181
	v_sub_f32_e32 v90, v90, v181
	v_sub_f32_e32 v91, v91, v181
	v_sub_f32_e32 v92, v92, v181
	v_sub_f32_e32 v93, v93, v181
	v_sub_f32_e32 v94, v94, v181
	v_sub_f32_e32 v66, v95, v181
	s_waitcnt lgkmcnt(1)
	v_mfma_f32_32x32x16_bf16 v[32:47], v[192:195], v[188:191], v[32:47]
	v_cvt_pk_bf16_f32 v188, v64, v65
	v_cvt_pk_bf16_f32 v189, v186, v67
	v_cvt_pk_bf16_f32 v190, v68, v69
	v_cvt_pk_bf16_f32 v191, v70, v71
	v_exp_f32_e32 v88, v88
	v_exp_f32_e32 v89, v89
	v_exp_f32_e32 v90, v90
	v_mfma_f32_32x32x16_bf16 v[0:15], v[192:195], v[188:191], v[0:15]
	ds_read2_b64 v[192:195], v183 offset0:60 offset1:62
	v_exp_f32_e32 v91, v91
	v_exp_f32_e32 v92, v92
	v_exp_f32_e32 v93, v93
	v_exp_f32_e32 v94, v94
	v_exp_f32_e32 v66, v66
	v_sub_f32_e32 v72, v72, v184
	v_mfma_f32_32x32x16_bf16 v[16:31], v[204:207], v[188:191], v[16:31]
	v_sub_f32_e32 v73, v73, v184
	v_sub_f32_e32 v74, v74, v184
	v_sub_f32_e32 v75, v75, v184
	v_sub_f32_e32 v76, v76, v184
	v_sub_f32_e32 v77, v77, v184
	v_sub_f32_e32 v78, v78, v184
	v_sub_f32_e32 v79, v79, v184
	v_exp_f32_e32 v72, v72
	v_exp_f32_e32 v73, v73
	v_exp_f32_e32 v74, v74
	v_exp_f32_e32 v75, v75
	v_exp_f32_e32 v76, v76
	v_exp_f32_e32 v77, v77
	v_exp_f32_e32 v78, v78
	v_exp_f32_e32 v79, v79
	v_cvt_pk_bf16_f32 v188, v88, v89
	v_cvt_pk_bf16_f32 v189, v90, v91
	v_cvt_pk_bf16_f32 v190, v92, v93
	v_cvt_pk_bf16_f32 v191, v94, v66
	s_andn2_b64 vcc, exec, s[10:11]
	s_waitcnt lgkmcnt(1)
	v_mfma_f32_32x32x16_bf16 v[48:63], v[196:199], v[188:191], v[48:63]
	s_waitcnt lgkmcnt(0)
	v_mfma_f32_32x32x16_bf16 v[32:47], v[192:195], v[188:191], v[32:47]
	v_cvt_pk_bf16_f32 v188, v72, v73
	v_cvt_pk_bf16_f32 v189, v74, v75
	v_cvt_pk_bf16_f32 v190, v76, v77
	v_cvt_pk_bf16_f32 v191, v78, v79
	s_nop 1
	v_mfma_f32_32x32x16_bf16 v[16:31], v[196:199], v[188:191], v[16:31]
	v_mfma_f32_32x32x16_bf16 v[0:15], v[192:195], v[188:191], v[0:15]
	s_cmp_lg_u32 s101, 0
	s_cbranch_scc1 .LBB0_417
	s_cbranch_vccnz .LBB0_417
	s_waitcnt vmcnt(0)
	s_add_u32 s10, s100, 0x8a00
	s_cmp_eq_u32 s10, 0x19e00
	s_cselect_b32 s10, 0, s10
	v_add3_u32 v95, s10, v175, v166
	v_add3_u32 v182, s10, v176, v166
	v_add_u32_e32 v183, 0x4800, v182
	ds_write_b128 v95, v[130:133]
	ds_write_b128 v95, v[134:137] offset:9216
	ds_write2_b64 v183, v[154:155], v[156:157] offset1:1
	v_add_u32_e32 v95, 0x4880, v182
	ds_write2_b64 v95, v[158:159], v[160:161] offset1:1
	s_branch .LBB0_417

; #define LAS __attribute__((address_space(3)))
; __device__ __forceinline__ int opaque_tid() { int t = threadIdx.x; asm volatile("" : "+v"(t)); return t; }
; #define AT_LOAD(t_) do { const bf16_t* kn = ksrc + (size_t)(t_) * AKT * INW; const bf16_t* vn = vsrc + (t_) * AKT; \
;         kreg0 = *(const u32x4*)kn; kreg1 = *(const u32x4*)(kn + (size_t)64 * INW); vreg0 = *(const u32x4*)vn; vreg1 = *(const u32x4*)(vn + 64); } while (0)
; template <int DK, bool IS_A>
; __device__ __forceinline__ void attn_unit(const Params& P, int l, LAS unsigned char* lds, int b, int grp, int qtok0, int nkeys) {
;     const int tid = opaque_tid(), lane = tid & 63, wave = tid >> 6, s = wave >> 2, wq = wave & 3, r32 = lane & 31, hi = lane >> 5;
;     const bf16_t* proj = (const bf16_t*)(P.ws + WS_PROJ);
;     bf16_t* mix = (bf16_t*)(P.ws + WS_H);
;     const int qcol = IS_A ? PA_Q + grp * 64 + s * 32 : PC_Q + (2 * grp + s) * 64;
;     const int kcol = IS_A ? PA_K + grp * 64 : PC_K + grp * 64;
;     const int koff = IS_A ? s * 32 : 0;
;     const bf16_t* VT = IS_A ? (const bf16_t*)(P.ws + WS_VTA) + ((size_t)(b * 4 + grp) * 64) * TT : (const bf16_t*)(P.ws + WS_VTC) + ((size_t)(b * 2 + grp) * 64) * TT;
;     const size_t qrow = (size_t)b * TT + qtok0 + wq * 64 + r32;
;     bf16x8 qa[DK / 16], qb[DK / 16];
; #pragma unroll
;     for (int i = 0; i < DK / 16; ++i) { qa[i] = *(const bf16x8*)(proj + qrow * INW + qcol + i * 16 + hi * 8); qb[i] = *(const bf16x8*)(proj + (qrow + 32) * INW + qcol + i * 16 + hi * 8); }
;     const int lrow = tid >> 3, lch = tid & 7;
;     const bf16_t* ksrc = proj + ((size_t)b * TT + lrow) * INW + kcol + lch * 8;
;     const bf16_t* vsrc = VT + (size_t)lrow * TT + lch * 8;
;     const int NT = nkeys / AKT;
;     u32x4 kreg0, kreg1, vreg0, vreg1;
;     ...
;     const int kfo = r32 * AK_PITCH + (koff + 8 * hi) * 2, vfo = AK_BYTES + r32 * AV_PITCH + 8 * hi;
;     AT_LOAD(0); AT_STORE(0);
;     __syncthreads();
;     float ma = -1e30f, mb = -1e30f, la = 0.f, lb_ = 0.f;
;     f32x16 oa0, oa1, ob0, ob1;
; #pragma unroll
;     for (int r = 0; r < 16; ++r) { oa0[r] = 0.f; oa1[r] = 0.f; ob0[r] = 0.f; ob1[r] = 0.f; }
;     ...
;         if (it < N_C) { attn_unit<64, false>(P, l, lds, it >> 4, (it >> 3) & 1, CTX + (it & 7) * 256, TT); continue; } it -= N_C;
.LBB0_440:
	s_andn2_b64 vcc, exec, s[10:11]
	s_cbranch_vccnz .LBB0_460
	s_add_i32 s8, s37, 0xffffff60
	s_lshr_b32 s15, s8, 4
	s_lshl_b32 s8, s37, 8
	s_bfe_u32 s18, s37, 0x10003
	s_and_b32 s9, s8, 0x700
	s_mul_i32 s8, s15, 0x900
	v_mov_b32_e32 v12, v200
	s_add_i32 s9, s9, s8
	s_lshl_b32 s11, s18, 6
	s_lshl_b32 s12, s15, 7
	v_ashrrev_i32_e32 v2, 3, v12
	s_or_b32 s11, s11, s12
	s_add_i32 s19, s9, 0x100
	s_mov_b32 s9, s65
	v_ashrrev_i32_e32 v3, 31, v2
	s_mul_i32 s64, s11, 0x900
	v_mov_b64_e32 v[0:1], s[56:57]
	v_lshl_add_u64 v[4:5], v[2:3], 0, s[8:9]
	s_lshl_b32 s10, s18, 7
	s_lshl_b64 s[12:13], s[64:65], 1
	v_mad_u64_u32 v[6:7], s[8:9], v4, s23, v[0:1]
	s_add_u32 s12, s20, s12
	v_readlane_b32 s7, v255, 5
	v_mad_i32_i24 v7, v5, s23, v7
	s_mov_b32 s11, s65
	v_lshlrev_b32_e32 v3, 4, v12
	s_addc_u32 s13, s7, s13
	v_lshl_add_u64 v[6:7], v[6:7], 0, s[10:11]
	v_and_b32_e32 v190, 0x70, v3
	v_mov_b32_e32 v191, v129
	v_lshl_add_u64 v[6:7], v[6:7], 0, v[190:191]
	v_mov_b64_e32 v[8:9], s[12:13]
	s_movk_i32 s7, 0x1000
	v_mad_i64_i32 v[8:9], s[8:9], v2, s27, v[8:9]
	v_add_co_u32_e32 v10, vcc, s7, v6
	s_mov_b32 s8, 0x59000
	s_nop 0
	v_addc_co_u32_e32 v11, vcc, 0, v7, vcc
	v_add_co_u32_e32 v6, vcc, s8, v6
	v_lshl_add_u64 v[8:9], v[8:9], 0, v[190:191]
	s_nop 0
	v_addc_co_u32_e32 v7, vcc, 0, v7, vcc
	global_load_dwordx4 v[130:133], v[10:11], off offset:512
	global_load_dwordx4 v[134:137], v[6:7], off offset:512
	global_load_dwordx4 v[138:141], v[8:9], off
	global_load_dwordx4 v[150:153], v[8:9], off offset:128
	v_ashrrev_i32_e32 v6, 2, v12
	v_and_b32_e32 v3, 0xc0, v12
	v_and_b32_e32 v13, 31, v12
	v_and_b32_e32 v6, 0xffffffc0, v6
	v_add_u32_e32 v188, s10, v6
	v_or3_b32 v128, s19, v3, v13
	v_bfe_u32 v14, v12, 5, 1
	v_mad_u64_u32 v[0:1], s[8:9], v128, s23, v[0:1]
	v_ashrrev_i32_e32 v189, 31, v188
	v_lshl_add_u64 v[0:1], v[188:189], 1, v[0:1]
	v_lshlrev_b32_e32 v192, 4, v14
	v_mov_b32_e32 v193, v129
	v_lshl_add_u64 v[0:1], v[0:1], 0, v[192:193]
	s_mov_b64 s[8:9], 0x1000
	v_add_co_u32_e32 v10, vcc, s7, v0
	v_lshl_add_u64 v[6:7], v[0:1], 0, s[8:9]
	s_mov_b64 s[8:9], 0x2d000
	v_addc_co_u32_e32 v11, vcc, 0, v1, vcc
	s_mov_b32 s7, 0x2d000
	v_lshl_add_u64 v[8:9], v[0:1], 0, s[8:9]
	v_add_co_u32_e32 v0, vcc, s7, v0
	s_movk_i32 s7, 0x90
	s_nop 0
	v_addc_co_u32_e32 v1, vcc, 0, v1, vcc
	global_load_dwordx4 v[142:145], v[10:11], off
	global_load_dwordx4 v[146:149], v[0:1], off
	global_load_dwordx4 v[154:157], v[6:7], off offset:32
	global_load_dwordx4 v[158:161], v[6:7], off offset:64
	global_load_dwordx4 v[162:165], v[8:9], off offset:32
	global_load_dwordx4 v[166:169], v[6:7], off offset:96
	global_load_dwordx4 v[170:173], v[8:9], off offset:64
	global_load_dwordx4 v[174:177], v[8:9], off offset:96
	v_mul_lo_u32 v179, v2, s7
	s_movk_i32 s7, 0x108
	v_and_b32_e32 v1, 63, v12
	v_mul_lo_u32 v180, v2, s7
	v_add3_u32 v0, 0, v179, v190
	s_movk_i32 s7, 0x78
	s_mul_i32 s9, s15, 0x48000
	s_mul_i32 s18, s18, 0x24000
	v_mad_u64_u32 v[6:7], s[12:13], v2, s7, v[0:1]
	s_add_i32 s64, s9, s18
	s_lshl_b64 s[12:13], s[64:65], 1
	s_add_u32 s12, s54, s12
	v_add_u32_e32 v3, 0x4800, v6
	s_addc_u32 s13, s55, s13
	s_waitcnt vmcnt(11)
	ds_write_b128 v0, v[130:133]
	s_waitcnt vmcnt(10)
	ds_write_b128 v0, v[134:137] offset:9216
	s_waitcnt vmcnt(9)
	ds_write2_b64 v3, v[138:139], v[140:141] offset1:1
	v_add_u32_e32 v0, 0x4880, v6
	s_waitcnt vmcnt(8)
	ds_write2_b64 v0, v[150:151], v[152:153] offset1:1
	v_lshlrev_b32_e32 v0, 2, v1
	s_add_u32 s10, s54, s10
	v_xor_b32_e32 v181, 0x80, v0
	v_mov_b64_e32 v[0:1], s[12:13]
	s_addc_u32 s11, s55, 0
	v_mad_i64_i32 v[194:195], s[12:13], v2, s27, v[0:1]
	v_mov_b64_e32 v[0:1], s[10:11]
	v_lshlrev_b32_e32 v186, 3, v14
	v_mad_u64_u32 v[196:197], s[10:11], v4, s23, v[0:1]
	v_mov_b32_e32 v14, v129
	v_mov_b32_e32 v15, v129
	v_mul_u32_u24_e32 v178, 0x90, v13
	v_mul_u32_u24_e32 v182, 0x108, v13
	v_mad_i32_i24 v197, v5, s23, v197
	v_mov_b32_e32 v0, v129
	v_mov_b32_e32 v1, v129
	v_mov_b32_e32 v2, v129
	v_mov_b32_e32 v3, v129
	v_mov_b32_e32 v4, v129
	v_mov_b32_e32 v5, v129
	v_mov_b32_e32 v6, v129
	v_mov_b32_e32 v7, v129
	v_mov_b32_e32 v8, v129
	v_mov_b32_e32 v9, v129
	v_mov_b32_e32 v10, v129
	v_mov_b32_e32 v11, v129
	v_mov_b32_e32 v12, v129
	v_mov_b32_e32 v13, v129
	v_mov_b64_e32 v[30:31], v[14:15]
	v_mov_b64_e32 v[46:47], v[14:15]
	v_mov_b64_e32 v[62:63], v[14:15]
	s_mov_b32 s8, 0
	v_mov_b32_e32 v198, 0
	v_mov_b32_e32 v184, 0xf149f2ca
	v_mov_b32_e32 v193, 0xf149f2ca
	v_mov_b32_e32 v183, 0
	v_mov_b64_e32 v[28:29], v[12:13]
	v_mov_b64_e32 v[26:27], v[10:11]
	v_mov_b64_e32 v[24:25], v[8:9]
	v_mov_b64_e32 v[22:23], v[6:7]
	v_mov_b64_e32 v[20:21], v[4:5]
	v_mov_b64_e32 v[18:19], v[2:3]
	v_mov_b64_e32 v[16:17], v[0:1]
	v_mov_b64_e32 v[44:45], v[12:13]
	v_mov_b64_e32 v[42:43], v[10:11]
	v_mov_b64_e32 v[40:41], v[8:9]
	v_mov_b64_e32 v[38:39], v[6:7]
	v_mov_b64_e32 v[36:37], v[4:5]
	v_mov_b64_e32 v[34:35], v[2:3]
	v_mov_b64_e32 v[32:33], v[0:1]
	v_mov_b64_e32 v[60:61], v[12:13]
	v_mov_b64_e32 v[58:59], v[10:11]
	v_mov_b64_e32 v[56:57], v[8:9]
	v_mov_b64_e32 v[54:55], v[6:7]
	v_mov_b64_e32 v[52:53], v[4:5]
	v_mov_b64_e32 v[50:51], v[2:3]
	v_mov_b64_e32 v[48:49], v[0:1]
	s_waitcnt lgkmcnt(0)
	s_waitcnt vmcnt(0)
	s_mov_b32 s100, 0
	v_readfirstlane_b32 s101, v200
	s_nop 3
	s_lshr_b32 s101, s101, 8
	s_barrier
	s_branch .LBB0_443
; template <int DK, bool IS_A>
; __device__ __forceinline__ void attn_unit(const Params& P, int l, LAS unsigned char* lds, int b, int grp, int qtok0, int nkeys) {
;     ...
;         if (t + 1 < NT) AT_STORE(buf ^ 1);
;         __syncthreads();
;     }
.LBB0_442:
	v_add_f32_e32 v95, 0, v96
	v_add_f32_e32 v95, v97, v95
	v_add_f32_e32 v95, v98, v95
	v_add_f32_e32 v95, v99, v95
	v_add_f32_e32 v95, v100, v95
	v_add_f32_e32 v95, v101, v95
	v_add_f32_e32 v95, v102, v95
	v_add_f32_e32 v95, v103, v95
	v_add_f32_e32 v95, v104, v95
	v_add_f32_e32 v95, v105, v95
	v_add_f32_e32 v95, v106, v95
	v_add_f32_e32 v95, v107, v95
	v_add_f32_e32 v95, v108, v95
	v_add_f32_e32 v95, v109, v95
	v_add_f32_e32 v95, v110, v95
	v_add_f32_e32 v95, v111, v95
	v_add_f32_e32 v64, v64, v95
	v_add_f32_e32 v64, v65, v64
	v_add_f32_e32 v64, v199, v64
	v_add_f32_e32 v64, v67, v64
	v_add_f32_e32 v64, v68, v64
	v_add_f32_e32 v64, v69, v64
	v_add_f32_e32 v64, v70, v64
	v_add_f32_e32 v64, v71, v64
	v_add_f32_e32 v64, v72, v64
	v_add_f32_e32 v64, v73, v64
	v_add_f32_e32 v64, v74, v64
	v_add_f32_e32 v64, v75, v64
	v_add_f32_e32 v64, v76, v64
	v_add_f32_e32 v64, v77, v64
	v_add_f32_e32 v64, v78, v64
	v_add_f32_e32 v64, v79, v64
	v_add_f32_e32 v183, v183, v64
	v_add_f32_e32 v64, 0, v112
	v_add_f32_e32 v64, v113, v64
	v_add_f32_e32 v64, v114, v64
	v_add_f32_e32 v64, v115, v64
	v_add_f32_e32 v64, v116, v64
	v_add_f32_e32 v64, v117, v64
	v_add_f32_e32 v64, v118, v64
	v_add_f32_e32 v64, v119, v64
	v_add_f32_e32 v64, v120, v64
	v_add_f32_e32 v64, v121, v64
	v_add_f32_e32 v64, v122, v64
	v_add_f32_e32 v64, v123, v64
	v_add_f32_e32 v64, v124, v64
	v_add_f32_e32 v64, v125, v64
	v_add_f32_e32 v64, v126, v64
	v_add_f32_e32 v64, v127, v64
	v_add_f32_e32 v64, v80, v64
	v_add_f32_e32 v64, v81, v64
	v_add_f32_e32 v64, v82, v64
	v_add_f32_e32 v64, v83, v64
	v_add_f32_e32 v64, v84, v64
	v_add_f32_e32 v64, v85, v64
	v_add_f32_e32 v64, v86, v64
	v_add_f32_e32 v64, v87, v64
	v_add_f32_e32 v64, v88, v64
	v_add_f32_e32 v64, v89, v64
	v_add_f32_e32 v64, v90, v64
	v_add_f32_e32 v64, v91, v64
	v_add_f32_e32 v64, v92, v64
	v_add_f32_e32 v64, v93, v64
	v_add_f32_e32 v64, v94, v64
	s_mov_b64 s[10:11], 0x100
	v_add_f32_e32 v64, v66, v64
	s_add_i32 s8, s8, 1
	v_lshl_add_u64 v[194:195], v[194:195], 0, s[10:11]
	s_mov_b64 s[10:11], 0xb0000
	v_add_f32_e32 v198, v198, v64
	v_lshl_add_u64 v[196:197], v[196:197], 0, s[10:11]
	s_waitcnt lgkmcnt(0)
	s_cmp_lg_u32 s101, 0
	s_cbranch_scc1 .Lattc_nobar
	s_barrier
.Lattc_nobar:
	s_add_u32 s100, s100, 0x8a00
	s_cmp_eq_u32 s100, 0x19e00
	s_cselect_b32 s100, 0, s100
	s_cmp_lg_u32 s8, 18
	s_cbranch_scc0 .LBB0_459

; #define LAS __attribute__((address_space(3)))
; template <int DK, bool IS_A>
; __device__ __forceinline__ void attn_unit(const Params& P, int l, LAS unsigned char* lds, int b, int grp, int qtok0, int nkeys) {
;     ...
;             const LAS unsigned char* kb = lds + buf * A_BUF + kfo + h * 64 * AK_PITCH;
;             const LAS unsigned char* vb = lds + buf * A_BUF + vfo + h * 128;
;             f32x16 pa[2], pb[2];
; #pragma unroll
;             for (int jj = 0; jj < 2; ++jj)
; #pragma unroll
;                 for (int r = 0; r < 16; ++r) { pa[jj][r] = 0.f; pb[jj][r] = 0.f; }
;             __builtin_amdgcn_s_setprio(1);
; #pragma unroll
;             for (int i = 0; i < DK / 16; ++i)
; #pragma unroll
;                 for (int jj = 0; jj < 2; ++jj) {
;                     const bf16x8 kf = *(const LAS bf16x8*)(kb + jj * 32 * AK_PITCH + i * 32);
;                     pa[jj] = __builtin_amdgcn_mfma_f32_32x32x16_bf16(kf, qa[i], pa[jj], 0, 0, 0);
;                     pb[jj] = __builtin_amdgcn_mfma_f32_32x32x16_bf16(kf, qb[i], pb[jj], 0, 0, 0);
;                 }
;             __builtin_amdgcn_s_setprio(0);
.LBB0_445:
	s_mov_b32 s12, s100
	v_add_u32_e32 v64, s12, v178
	v_add_u32_e32 v199, v64, v192
	s_setprio 1
	ds_read_b128 v[64:67], v199
	ds_read_b128 v[204:207], v199 offset:32
	s_waitcnt lgkmcnt(1)
	v_mfma_f32_32x32x16_bf16 v[112:127], v[64:67], v[142:145], 0
	v_mfma_f32_32x32x16_bf16 v[96:111], v[64:67], v[146:149], 0
	ds_read_b128 v[64:67], v199 offset:4608
	s_waitcnt lgkmcnt(1)
	v_mfma_f32_32x32x16_bf16 v[112:127], v[204:207], v[154:157], v[112:127]
	v_mfma_f32_32x32x16_bf16 v[96:111], v[204:207], v[162:165], v[96:111]
	ds_read_b128 v[204:207], v199 offset:4640
	s_waitcnt lgkmcnt(1)
	v_mfma_f32_32x32x16_bf16 v[80:95], v[64:67], v[142:145], 0
	v_mfma_f32_32x32x16_bf16 v[64:79], v[64:67], v[146:149], 0
	s_waitcnt lgkmcnt(0)
	v_mfma_f32_32x32x16_bf16 v[80:95], v[204:207], v[154:157], v[80:95]
	v_mfma_f32_32x32x16_bf16 v[64:79], v[204:207], v[162:165], v[64:79]
	ds_read_b128 v[204:207], v199 offset:64
	s_waitcnt lgkmcnt(0)
	v_mfma_f32_32x32x16_bf16 v[112:127], v[204:207], v[158:161], v[112:127]
	v_mfma_f32_32x32x16_bf16 v[96:111], v[204:207], v[170:173], v[96:111]
	ds_read_b128 v[204:207], v199 offset:4672
	s_waitcnt lgkmcnt(0)
	v_mfma_f32_32x32x16_bf16 v[80:95], v[204:207], v[158:161], v[80:95]
	v_mfma_f32_32x32x16_bf16 v[64:79], v[204:207], v[170:173], v[64:79]
	ds_read_b128 v[204:207], v199 offset:96
	s_waitcnt lgkmcnt(0)
	v_mfma_f32_32x32x16_bf16 v[112:127], v[204:207], v[166:169], v[112:127]
	v_mfma_f32_32x32x16_bf16 v[96:111], v[204:207], v[174:177], v[96:111]
	ds_read_b128 v[204:207], v199 offset:4704
	s_waitcnt lgkmcnt(0)
	v_mfma_f32_32x32x16_bf16 v[80:95], v[204:207], v[166:169], v[80:95]
	v_mfma_f32_32x32x16_bf16 v[64:79], v[204:207], v[174:177], v[64:79]
	s_setprio 0
	s_nop 9
	v_max_f32_e32 v185, v80, v80
	v_max_f32_e32 v187, v112, v112
	v_max_f32_e32 v185, v187, v185
	v_max3_f32 v187, v81, v114, v82
	v_max3_f32 v185, v185, v113, v115
	v_max3_f32 v187, v187, v116, v84
	v_max3_f32 v185, v185, v83, v117
	v_max3_f32 v187, v187, v118, v86
	v_max3_f32 v185, v185, v85, v119
	v_max3_f32 v187, v187, v120, v88
	v_max3_f32 v185, v185, v87, v121
	v_max3_f32 v187, v187, v122, v90
	v_max3_f32 v185, v185, v89, v123
	v_max3_f32 v187, v187, v124, v92
	v_max3_f32 v185, v185, v91, v125
	v_max3_f32 v187, v187, v126, v94
	v_max3_f32 v185, v185, v93, v127
	v_max3_f32 v185, v185, v95, v187
	ds_bpermute_b32 v187, v181, v185
	s_waitcnt lgkmcnt(0)
	v_max3_f32 v205, v184, v185, v187
	v_cmp_gt_f32_e32 vcc, v205, v184
	s_cbranch_vccz .LBB0_447
	v_sub_f32_e32 v184, v184, v205
	v_exp_f32_e32 v184, v184
	s_nop 0
	v_pk_mul_f32 v[62:63], v[62:63], v[184:185] op_sel_hi:[1,0]
	v_pk_mul_f32 v[60:61], v[60:61], v[184:185] op_sel_hi:[1,0]
	v_pk_mul_f32 v[58:59], v[58:59], v[184:185] op_sel_hi:[1,0]
	v_pk_mul_f32 v[56:57], v[56:57], v[184:185] op_sel_hi:[1,0]
	v_pk_mul_f32 v[54:55], v[54:55], v[184:185] op_sel_hi:[1,0]
	v_pk_mul_f32 v[52:53], v[52:53], v[184:185] op_sel_hi:[1,0]
	v_pk_mul_f32 v[50:51], v[50:51], v[184:185] op_sel_hi:[1,0]
	v_pk_mul_f32 v[48:49], v[48:49], v[184:185] op_sel_hi:[1,0]
	v_pk_mul_f32 v[46:47], v[46:47], v[184:185] op_sel_hi:[1,0]
	v_pk_mul_f32 v[44:45], v[44:45], v[184:185] op_sel_hi:[1,0]
	v_pk_mul_f32 v[42:43], v[42:43], v[184:185] op_sel_hi:[1,0]
	v_pk_mul_f32 v[40:41], v[40:41], v[184:185] op_sel_hi:[1,0]
	v_pk_mul_f32 v[38:39], v[38:39], v[184:185] op_sel_hi:[1,0]
	v_pk_mul_f32 v[36:37], v[36:37], v[184:185] op_sel_hi:[1,0]
	v_pk_mul_f32 v[34:35], v[34:35], v[184:185] op_sel_hi:[1,0]
	v_pk_mul_f32 v[32:33], v[32:33], v[184:185] op_sel_hi:[1,0]
	v_mul_f32_e32 v198, v198, v184
	s_branch .LBB0_448

; template <int DK, bool IS_A>
; __device__ __forceinline__ void attn_unit(const Params& P, int l, LAS unsigned char* lds, int b, int grp, int qtok0, int nkeys) {
;     ...
;         if (t + 1 < NT) AT_STORE(buf ^ 1);
.LBB0_457:
	s_cmp_eq_u32 s101, 0
	s_cbranch_scc1 .Lattc_w03
	s_cmp_eq_u64 s[10:11], 0
	s_cbranch_scc1 .Lattc_pubdone
	s_add_u32 vcc_lo, s100, 0x8a00
	s_cmp_eq_u32 vcc_lo, 0x19e00
	s_cselect_b32 vcc_lo, 0, vcc_lo
	s_waitcnt vmcnt(0)
	v_add3_u32 v216, vcc_lo, v179, v190
	v_add3_u32 v217, vcc_lo, v180, v190
	v_add_u32_e32 v218, 0x4800, v217
	ds_write_b128 v216, v[130:133]
	ds_write_b128 v216, v[134:137] offset:9216
	ds_write2_b64 v218, v[138:139], v[140:141] offset1:1
	v_add_u32_e32 v216, 0x4880, v217
	ds_write2_b64 v216, v[150:151], v[152:153] offset1:1

; #define LAS __attribute__((address_space(3)))
; __device__ __forceinline__ unsigned pk2(float lo, float hi) { f32x2_t v = {lo, hi}; bf16x2_t b = __builtin_convertvector(v, bf16x2_t); return __builtin_bit_cast(unsigned, b); }
; template <int DK, bool IS_A>
; __device__ __forceinline__ void attn_unit(const Params& P, int l, LAS unsigned char* lds, int b, int grp, int qtok0, int nkeys) {
;     ...
; #pragma unroll
;             for (int ks = 0; ks < 4; ++ks) {
;                 const int o8 = 8 * (ks & 1);
;                 u32x4 w; const f32x16& xa = pa[ks >> 1]; const f32x16& xb = pb[ks >> 1];
;                 w.x = pk2(xa[o8], xa[o8 + 1]); w.y = pk2(xa[o8 + 2], xa[o8 + 3]); w.z = pk2(xa[o8 + 4], xa[o8 + 5]); w.w = pk2(xa[o8 + 6], xa[o8 + 7]);
;                 const bf16x8 pfa = __builtin_bit_cast(bf16x8, w);
;                 w.x = pk2(xb[o8], xb[o8 + 1]); w.y = pk2(xb[o8 + 2], xb[o8 + 3]); w.z = pk2(xb[o8 + 4], xb[o8 + 5]); w.w = pk2(xb[o8 + 6], xb[o8 + 7]);
;                 const bf16x8 pfb = __builtin_bit_cast(bf16x8, w);
;                 const u32x2 a0 = *(const LAS u32x2*)(vb + ks * 32), a1 = *(const LAS u32x2*)(vb + ks * 32 + 16);
;                 const u32x2 c0 = *(const LAS u32x2*)(vb + 32 * AV_PITCH + ks * 32), c1 = *(const LAS u32x2*)(vb + 32 * AV_PITCH + ks * 32 + 16);
;                 const bf16x8 v0 = __builtin_bit_cast(bf16x8, ((u32x4){a0.x, a0.y, a1.x, a1.y})), v1 = __builtin_bit_cast(bf16x8, ((u32x4){c0.x, c0.y, c1.x, c1.y}));
;                 oa0 = __builtin_amdgcn_mfma_f32_32x32x16_bf16(v0, pfa, oa0, 0, 0, 0);
;                 oa1 = __builtin_amdgcn_mfma_f32_32x32x16_bf16(v1, pfa, oa1, 0, 0, 0);
;                 ob0 = __builtin_amdgcn_mfma_f32_32x32x16_bf16(v0, pfb, ob0, 0, 0, 0);
;                 ob1 = __builtin_amdgcn_mfma_f32_32x32x16_bf16(v1, pfb, ob1, 0, 0, 0);
;             }
;         }
;         if (t + 1 < NT) AT_STORE(buf ^ 1);
.Lattc_w03:
	ds_read2_b64 v[204:207], v185 offset0:16 offset1:18
	ds_read2_b64 v[212:215], v187 offset0:48 offset1:50
	v_sub_f32_e32 v112, v112, v184
	v_sub_f32_e32 v113, v113, v184
	v_sub_f32_e32 v114, v114, v184
	v_sub_f32_e32 v115, v115, v184
	v_sub_f32_e32 v116, v116, v184
	v_sub_f32_e32 v117, v117, v184
	v_sub_f32_e32 v118, v118, v184
	v_sub_f32_e32 v119, v119, v184
	v_exp_f32_e32 v112, v112
	v_exp_f32_e32 v113, v113
	v_exp_f32_e32 v114, v114
	v_exp_f32_e32 v115, v115
	v_exp_f32_e32 v116, v116
	v_exp_f32_e32 v117, v117
	v_exp_f32_e32 v118, v118
	v_exp_f32_e32 v119, v119
	v_sub_f32_e32 v96, v96, v193
	v_sub_f32_e32 v97, v97, v193
	v_sub_f32_e32 v98, v98, v193
	v_sub_f32_e32 v99, v99, v193
	v_sub_f32_e32 v100, v100, v193
	v_sub_f32_e32 v101, v101, v193
	v_sub_f32_e32 v102, v102, v193
	v_sub_f32_e32 v103, v103, v193
	v_exp_f32_e32 v96, v96
	v_exp_f32_e32 v97, v97
	v_exp_f32_e32 v98, v98
	v_exp_f32_e32 v99, v99
	v_exp_f32_e32 v100, v100
	v_exp_f32_e32 v101, v101
	v_exp_f32_e32 v102, v102
	v_exp_f32_e32 v103, v103
	v_cvt_pk_bf16_f32 v208, v112, v113
	v_cvt_pk_bf16_f32 v209, v114, v115
	v_cvt_pk_bf16_f32 v210, v116, v117
	v_cvt_pk_bf16_f32 v211, v118, v119
	v_sub_f32_e32 v120, v120, v184
	v_sub_f32_e32 v121, v121, v184
	s_waitcnt lgkmcnt(1)
	v_mfma_f32_32x32x16_bf16 v[48:63], v[204:207], v[208:211], v[48:63]
	v_sub_f32_e32 v122, v122, v184
	v_sub_f32_e32 v123, v123, v184
	v_sub_f32_e32 v124, v124, v184
	v_sub_f32_e32 v125, v125, v184
	v_sub_f32_e32 v126, v126, v184
	v_sub_f32_e32 v127, v127, v184
	v_exp_f32_e32 v120, v120
	s_waitcnt lgkmcnt(0)
	v_mfma_f32_32x32x16_bf16 v[32:47], v[212:215], v[208:211], v[32:47]
	v_cvt_pk_bf16_f32 v208, v96, v97
	v_cvt_pk_bf16_f32 v209, v98, v99
	v_cvt_pk_bf16_f32 v210, v100, v101
	v_cvt_pk_bf16_f32 v211, v102, v103
	v_exp_f32_e32 v121, v121
	v_exp_f32_e32 v122, v122
	v_exp_f32_e32 v123, v123
	v_mfma_f32_32x32x16_bf16 v[16:31], v[204:207], v[208:211], v[16:31]
	ds_read2_b64 v[204:207], v185 offset0:20 offset1:22
	v_exp_f32_e32 v124, v124
	v_exp_f32_e32 v125, v125
	v_exp_f32_e32 v126, v126
	v_exp_f32_e32 v127, v127
	v_sub_f32_e32 v104, v104, v193
	v_sub_f32_e32 v105, v105, v193
	v_mfma_f32_32x32x16_bf16 v[0:15], v[212:215], v[208:211], v[0:15]
	ds_read2_b64 v[212:215], v187 offset0:52 offset1:54
	v_sub_f32_e32 v106, v106, v193
	v_sub_f32_e32 v107, v107, v193
	v_sub_f32_e32 v108, v108, v193
	v_sub_f32_e32 v109, v109, v193
	v_sub_f32_e32 v110, v110, v193
	v_sub_f32_e32 v111, v111, v193
	v_exp_f32_e32 v104, v104
	v_exp_f32_e32 v105, v105
	v_exp_f32_e32 v106, v106
	v_exp_f32_e32 v107, v107
	v_exp_f32_e32 v108, v108
	v_exp_f32_e32 v109, v109
	v_exp_f32_e32 v110, v110
	v_exp_f32_e32 v111, v111
	v_cvt_pk_bf16_f32 v208, v120, v121
	v_cvt_pk_bf16_f32 v209, v122, v123
	v_cvt_pk_bf16_f32 v210, v124, v125
	v_cvt_pk_bf16_f32 v211, v126, v127
	v_sub_f32_e32 v66, v66, v193
	v_exp_f32_e32 v199, v66
	s_waitcnt lgkmcnt(1)
	v_mfma_f32_32x32x16_bf16 v[48:63], v[204:207], v[208:211], v[48:63]
	v_sub_f32_e32 v66, v67, v193
	v_exp_f32_e32 v67, v66
	v_sub_f32_e32 v66, v68, v193
	v_exp_f32_e32 v68, v66
	v_sub_f32_e32 v66, v69, v193
	v_sub_f32_e32 v80, v80, v184
	v_sub_f32_e32 v81, v81, v184
	s_waitcnt lgkmcnt(0)
	v_mfma_f32_32x32x16_bf16 v[32:47], v[212:215], v[208:211], v[32:47]
	v_cvt_pk_bf16_f32 v208, v104, v105
	v_cvt_pk_bf16_f32 v209, v106, v107
	v_cvt_pk_bf16_f32 v210, v108, v109
	v_cvt_pk_bf16_f32 v211, v110, v111
	v_sub_f32_e32 v82, v82, v184
	v_sub_f32_e32 v83, v83, v184
	v_sub_f32_e32 v84, v84, v184
	v_mfma_f32_32x32x16_bf16 v[16:31], v[204:207], v[208:211], v[16:31]
	ds_read2_b64 v[204:207], v185 offset0:24 offset1:26
	v_sub_f32_e32 v85, v85, v184
	v_sub_f32_e32 v86, v86, v184
	v_sub_f32_e32 v87, v87, v184
	v_exp_f32_e32 v69, v66
	v_sub_f32_e32 v66, v70, v193
	v_exp_f32_e32 v80, v80
	v_mfma_f32_32x32x16_bf16 v[0:15], v[212:215], v[208:211], v[0:15]
	ds_read2_b64 v[212:215], v187 offset0:56 offset1:58
	v_exp_f32_e32 v81, v81
	v_exp_f32_e32 v82, v82
	v_exp_f32_e32 v83, v83
	v_exp_f32_e32 v84, v84
	v_exp_f32_e32 v85, v85
	v_exp_f32_e32 v86, v86
	v_exp_f32_e32 v87, v87
	v_sub_f32_e32 v64, v64, v193
	v_sub_f32_e32 v65, v65, v193
	v_exp_f32_e32 v70, v66
	v_sub_f32_e32 v66, v71, v193
	v_exp_f32_e32 v64, v64
	v_exp_f32_e32 v65, v65
	v_exp_f32_e32 v71, v66
	v_cvt_pk_bf16_f32 v208, v80, v81
	v_cvt_pk_bf16_f32 v209, v82, v83
	v_cvt_pk_bf16_f32 v210, v84, v85
	v_cvt_pk_bf16_f32 v211, v86, v87
	v_sub_f32_e32 v88, v88, v184
	v_sub_f32_e32 v89, v89, v184
	s_waitcnt lgkmcnt(1)
	v_mfma_f32_32x32x16_bf16 v[48:63], v[204:207], v[208:211], v[48:63]
	v_sub_f32_e32 v90, v90, v184
	v_sub_f32_e32 v91, v91, v184
	v_sub_f32_e32 v92, v92, v184
	v_sub_f32_e32 v93, v93, v184
	v_sub_f32_e32 v94, v94, v184
	v_sub_f32_e32 v66, v95, v184
	v_exp_f32_e32 v88, v88
	s_waitcnt lgkmcnt(0)
	v_mfma_f32_32x32x16_bf16 v[32:47], v[212:215], v[208:211], v[32:47]
	v_cvt_pk_bf16_f32 v208, v64, v65
	v_cvt_pk_bf16_f32 v209, v199, v67
	v_cvt_pk_bf16_f32 v210, v68, v69
	v_cvt_pk_bf16_f32 v211, v70, v71
	v_exp_f32_e32 v89, v89
	v_exp_f32_e32 v90, v90
	v_exp_f32_e32 v91, v91
	v_mfma_f32_32x32x16_bf16 v[16:31], v[204:207], v[208:211], v[16:31]
	ds_read2_b64 v[204:207], v185 offset0:28 offset1:30
	v_exp_f32_e32 v92, v92
	v_exp_f32_e32 v93, v93
	v_exp_f32_e32 v94, v94
	v_exp_f32_e32 v66, v66
	v_sub_f32_e32 v72, v72, v193
	v_sub_f32_e32 v73, v73, v193
	v_mfma_f32_32x32x16_bf16 v[0:15], v[212:215], v[208:211], v[0:15]
	ds_read2_b64 v[212:215], v187 offset0:60 offset1:62
	v_sub_f32_e32 v74, v74, v193
	v_sub_f32_e32 v75, v75, v193
	v_sub_f32_e32 v76, v76, v193
	v_sub_f32_e32 v77, v77, v193
	v_sub_f32_e32 v78, v78, v193
	v_sub_f32_e32 v79, v79, v193
	v_exp_f32_e32 v72, v72
	v_exp_f32_e32 v73, v73
	v_exp_f32_e32 v74, v74
	v_exp_f32_e32 v75, v75
	v_exp_f32_e32 v76, v76
	v_exp_f32_e32 v77, v77
	v_exp_f32_e32 v78, v78
	v_exp_f32_e32 v79, v79
	v_cvt_pk_bf16_f32 v208, v88, v89
	v_cvt_pk_bf16_f32 v209, v90, v91
	v_cvt_pk_bf16_f32 v210, v92, v93
	v_cvt_pk_bf16_f32 v211, v94, v66
	s_andn2_b64 vcc, exec, s[10:11]
	s_waitcnt lgkmcnt(1)
	v_mfma_f32_32x32x16_bf16 v[48:63], v[204:207], v[208:211], v[48:63]
	s_waitcnt lgkmcnt(0)
	v_mfma_f32_32x32x16_bf16 v[32:47], v[212:215], v[208:211], v[32:47]
	v_cvt_pk_bf16_f32 v208, v72, v73
	v_cvt_pk_bf16_f32 v209, v74, v75
	v_cvt_pk_bf16_f32 v210, v76, v77
	v_cvt_pk_bf16_f32 v211, v78, v79
	s_nop 1
	v_mfma_f32_32x32x16_bf16 v[16:31], v[204:207], v[208:211], v[16:31]
	v_mfma_f32_32x32x16_bf16 v[0:15], v[212:215], v[208:211], v[0:15]
	s_cmp_lg_u32 s101, 0
	s_cbranch_scc1 .LBB0_442
	s_cbranch_vccnz .LBB0_442
	s_waitcnt vmcnt(0)
	s_add_u32 s9, s100, 0x8a00
	s_cmp_eq_u32 s9, 0x19e00
	s_cselect_b32 s9, 0, s9
	v_add3_u32 v95, s9, v179, v190
	v_add3_u32 v185, s9, v180, v190
	v_add_u32_e32 v187, 0x4800, v185
	ds_write_b128 v95, v[130:133]
	ds_write_b128 v95, v[134:137] offset:9216
	ds_write2_b64 v187, v[138:139], v[140:141] offset1:1
	v_add_u32_e32 v95, 0x4880, v185
	ds_write2_b64 v95, v[150:151], v[152:153] offset1:1
	s_branch .LBB0_442

; #define LAS __attribute__((address_space(3)))
; __global__ void __launch_bounds__(512, 2) hybrid_fwd(Params Parg) {
;     extern __shared__ __attribute__((aligned(16))) unsigned char lds[];
;     cg::grid_group grid = cg::this_grid();
;     LAS unsigned char* ldsl = (LAS unsigned char*)lds;
;     volatile LAS unsigned* bst = (volatile LAS unsigned*)(ldsl + LDS_MISC + 64);
;     if (threadIdx.x == 0) { bst[0] = 0u; bst[1] = 0u; }
	.amdhsa_kernel _Z10hybrid_fwd6Params
		.amdhsa_group_segment_fixed_size 0
		.amdhsa_private_segment_fixed_size 0
		.amdhsa_kernarg_size 424
		.amdhsa_user_sgpr_count 2
		.amdhsa_user_sgpr_dispatch_ptr 0
		.amdhsa_user_sgpr_queue_ptr 0
		.amdhsa_user_sgpr_kernarg_segment_ptr 1
		.amdhsa_user_sgpr_dispatch_id 0
		.amdhsa_user_sgpr_kernarg_preload_length 0
		.amdhsa_user_sgpr_kernarg_preload_offset 0
		.amdhsa_user_sgpr_private_segment_size 0
		.amdhsa_uses_dynamic_stack 0
		.amdhsa_enable_private_segment 0
		.amdhsa_system_sgpr_workgroup_id_x 1
		.amdhsa_system_sgpr_workgroup_id_y 0
		.amdhsa_system_sgpr_workgroup_id_z 0
		.amdhsa_system_sgpr_workgroup_info 0
		.amdhsa_system_vgpr_workitem_id 2
		.amdhsa_next_free_vgpr 256
		.amdhsa_next_free_sgpr 102
		.amdhsa_accum_offset 256
		.amdhsa_reserve_vcc 1
		.amdhsa_float_round_mode_32 0
		.amdhsa_float_round_mode_16_64 0
		.amdhsa_float_denorm_mode_32 3
		.amdhsa_float_denorm_mode_16_64 3
		.amdhsa_dx10_clamp 1
		.amdhsa_ieee_mode 1
		.amdhsa_fp16_overflow 0
		.amdhsa_tg_split 0
		.amdhsa_exception_fp_ieee_invalid_op 0
		.amdhsa_exception_fp_denorm_src 0
		.amdhsa_exception_fp_ieee_div_zero 0
		.amdhsa_exception_fp_ieee_overflow 0
		.amdhsa_exception_fp_ieee_underflow 0
		.amdhsa_exception_fp_ieee_inexact 0
		.amdhsa_exception_int_div_zero 0
	.end_amdhsa_kernel

; __global__ void __launch_bounds__(512, 2) hybrid_fwd(Params Parg) {
;     extern __shared__ __attribute__((aligned(16))) unsigned char lds[];
amdhsa.kernels:
  - .agpr_count:     0
    .args:
      - .offset:         0
        .size:           168
        .value_kind:     by_value
      - .offset:         168
        .size:           4
        .value_kind:     hidden_block_count_x
      - .offset:         172
        .size:           4
        .value_kind:     hidden_block_count_y
      - .offset:         176
        .size:           4
        .value_kind:     hidden_block_count_z
      - .offset:         180
        .size:           2
        .value_kind:     hidden_group_size_x
      - .offset:         182
        .size:           2
        .value_kind:     hidden_group_size_y
      - .offset:         184
        .size:           2
        .value_kind:     hidden_group_size_z
      - .offset:         186
        .size:           2
        .value_kind:     hidden_remainder_x
      - .offset:         188
        .size:           2
        .value_kind:     hidden_remainder_y
      - .offset:         190
        .size:           2
        .value_kind:     hidden_remainder_z
      - .offset:         208
        .size:           8
        .value_kind:     hidden_global_offset_x
      - .offset:         216
        .size:           8
        .value_kind:     hidden_global_offset_y
      - .offset:         224
        .size:           8
        .value_kind:     hidden_global_offset_z
      - .offset:         232
        .size:           2
        .value_kind:     hidden_grid_dims
      - .offset:         256
        .size:           8
        .value_kind:     hidden_multigrid_sync_arg
      - .offset:         288
        .size:           4
        .value_kind:     hidden_dynamic_lds_size
    .group_segment_fixed_size: 0
    .kernarg_segment_align: 8
    .kernarg_segment_size: 424
    .language:       OpenCL C
    .language_version:
      - 2
      - 0
    .max_flat_workgroup_size: 512
    .name:           _Z10hybrid_fwd6Params
    .private_segment_fixed_size: 0
    .sgpr_count:     108
    .sgpr_spill_count: 187
    .symbol:         _Z10hybrid_fwd6Params.kd
    .uniform_work_group_size: 1
    .uses_dynamic_stack: false
    .vgpr_count:     256
    .vgpr_spill_count: 0
    .wavefront_size: 64
